# also phase-3 A-fragment reads inside MFMA(P2); stage A(1,0) first in phase 4; waits 4/6/8/6
# baseline (speedup 1.0000x reference)
; #define PG8_STAGE(bufoff, gbase, voff) do { _Pragma("unroll") for (int _i = 0; _i < 2; ++_i) \
;         __builtin_amdgcn_global_load_lds((const unsigned*)((const char*)(gbase) + (voff)[_i]), (PG8_LAS unsigned*)(lds + (bufoff) + ldsw + _i * 8192), 16, 0, 0); } while (0)
; #define PG8_LDA(dst, b, h) do { _Pragma("unroll") for (int m = 0; m < 4; ++m) _Pragma("unroll") for (int k = 0; k < 2; ++k) dst[m][k] = *(const PG8_LAS bf16x8*)(lds + PG8_SA(b, h) + aoff + m * 2048 + k * 1024); } while (0)
; #define PG8_LDB(dst, b, h) do { _Pragma("unroll") for (int n = 0; n < 2; ++n) _Pragma("unroll") for (int k = 0; k < 2; ++k) dst[n][k] = *(const PG8_LAS bf16x8*)(lds + PG8_SB(b, h) + boff + n * 2048 + k * 1024); } while (0)
; #define PG8_MMA(ai, bj, At, Bt) do { __builtin_amdgcn_s_setprio(1); _Pragma("unroll") for (int m = 0; m < 4; ++m) _Pragma("unroll") for (int n = 0; n < 2; ++n) _Pragma("unroll") for (int k = 0; k < 2; ++k) \
;         acc[ai][bj][m][n] = __builtin_amdgcn_mfma_f32_16x16x32_bf16(Bt[n][k], At[m][k], acc[ai][bj][m][n], 0, 0, 0); __builtin_amdgcn_s_setprio(0); } while (0)
; #define PG8_WAIT_V(n) asm volatile("s_waitcnt vmcnt(" #n ")" ::: "memory")
; #define PG8_BAR __builtin_amdgcn_s_barrier()
; template <class Epi, class Sched, bool ALIGN_EPI = true, bool SP2 = true>
; __device__ __forceinline__ void gemm_phase(PG8_LAS unsigned char* lds, const Gemm g, const Sched& S, const Epi& E, const int tid) {
;     ...
;         for (int t = 0; t < nt; t += 2) {
;             const bool last = (t == nt - 2);
;             const char* a1 = cA + (size_t)(t + 1) * kstep;
;             const char* a2 = last ? nA : cA + (size_t)(t + 2) * kstep; const char* b2 = last ? nB : cB + (size_t)(t + 2) * kstep;
;             const char* a3 = a2 + kstep; const char* b3 = b2 + kstep;
;             if (last && has_next) S.a_ready(nxt);
;             if constexpr (SP2) {
;             PG8_LDB(B0, 0, 0); PG8_LDB(B1, 0, 1); PG8_SCHED; PG8_LDA(At, 0, 0); PG8_STAGE(PG8_SA(1, 1), a1 + hstepA, voffA);
;             PG8_WAIT_V(8); PG8_WAIT_L(0); PG8_BAR; PG8_MMA(0, 0, At, B0); PG8_MMA(0, 1, At, B1); PG8_BAR; PG8_SCHED;
;             PG8_LDA(At, 0, 1); PG8_STAGE(PG8_SB(0, 0), b2, voffB); PG8_STAGE(PG8_SB(0, 1), b2 + hstepB, voffB); PG8_STAGE(PG8_SA(0, 0), a2, voffA);
;             PG8_WAIT_V(8); PG8_WAIT_L(0); PG8_BAR; PG8_MMA(1, 0, At, B0); PG8_MMA(1, 1, At, B1); PG8_BAR; PG8_SCHED;
.LBB0_381:
	s_add_u32 s25, s62, 0xfff80080
	s_addc_u32 s26, s63, -1
	s_add_i32 s27, 0, 0x10000
	s_cmp_eq_u32 s24, 28
	s_cselect_b32 s69, s18, s26
	s_cselect_b32 s68, s19, s25
	s_cselect_b32 s67, s20, s23
	s_cselect_b32 s66, s21, s22
	s_add_i32 s25, 0, 0x14000
	v_add_u32_e32 v158, s27, v163
	v_add_u32_e32 v165, s25, v163
	ds_read_b128 v[146:149], v158
	ds_read_b128 v[150:153], v158 offset:1024
	ds_read_b128 v[154:157], v158 offset:2048
	ds_read_b128 v[158:161], v158 offset:3072
	ds_read_b128 v[166:169], v165
	ds_read_b128 v[170:173], v165 offset:1024
	ds_read_b128 v[174:177], v165 offset:2048
	ds_read_b128 v[178:181], v165 offset:3072
	s_add_i32 m0, s82, 0xc000
	ds_read_b128 v[182:185], v164
	ds_read_b128 v[186:189], v164 offset:1024
	ds_read_b128 v[190:193], v164 offset:2048
	ds_read_b128 v[194:197], v164 offset:3072
	ds_read_b128 v[206:209], v164 offset:4096
	ds_read_b128 v[210:213], v164 offset:5120
	ds_read_b128 v[222:225], v164 offset:6144
	ds_read_b128 v[226:229], v164 offset:7168
	global_load_lds_dwordx4 v142, s[62:63]
	s_add_i32 m0, s82, 0xe000
	s_nop 0
	global_load_lds_dwordx4 v144, s[62:63]
	s_waitcnt vmcnt(4)
	s_waitcnt lgkmcnt(0)
	s_barrier
	s_setprio 1
	s_waitcnt lgkmcnt(0)
	v_mfma_f32_16x16x32_bf16 v[126:129], v[146:149], v[182:185], v[126:129]
	v_mfma_f32_16x16x32_bf16 v[122:125], v[154:157], v[182:185], v[122:125]
	ds_read_b128 v[200:203], v164 offset:16384
	v_mfma_f32_16x16x32_bf16 v[110:113], v[146:149], v[190:193], v[110:113]
	v_mfma_f32_16x16x32_bf16 v[106:109], v[154:157], v[190:193], v[106:109]
	v_mfma_f32_16x16x32_bf16 v[92:95], v[146:149], v[206:209], v[92:95]
	v_mfma_f32_16x16x32_bf16 v[88:91], v[154:157], v[206:209], v[88:91]
	ds_read_b128 v[218:221], v164 offset:17408
	v_mfma_f32_16x16x32_bf16 v[76:79], v[146:149], v[222:225], v[76:79]
	v_mfma_f32_16x16x32_bf16 v[72:75], v[154:157], v[222:225], v[72:75]
	v_mfma_f32_16x16x32_bf16 v[126:129], v[150:153], v[186:189], v[126:129]
	v_mfma_f32_16x16x32_bf16 v[122:125], v[158:161], v[186:189], v[122:125]
	ds_read_b128 v[230:233], v164 offset:18432
	v_mfma_f32_16x16x32_bf16 v[110:113], v[150:153], v[194:197], v[110:113]
	v_mfma_f32_16x16x32_bf16 v[106:109], v[158:161], v[194:197], v[106:109]
	v_mfma_f32_16x16x32_bf16 v[92:95], v[150:153], v[210:213], v[92:95]
	v_mfma_f32_16x16x32_bf16 v[88:91], v[158:161], v[210:213], v[88:91]
	ds_read_b128 v[234:237], v164 offset:19456
	v_mfma_f32_16x16x32_bf16 v[76:79], v[150:153], v[226:229], v[76:79]
	v_mfma_f32_16x16x32_bf16 v[72:75], v[158:161], v[226:229], v[72:75]
	s_setprio 0
	s_setprio 1
	v_mfma_f32_16x16x32_bf16 v[118:121], v[166:169], v[182:185], v[118:121]
	v_mfma_f32_16x16x32_bf16 v[114:117], v[174:177], v[182:185], v[114:117]
	ds_read_b128 v[238:241], v164 offset:20480
	v_mfma_f32_16x16x32_bf16 v[102:105], v[166:169], v[190:193], v[102:105]
	v_mfma_f32_16x16x32_bf16 v[98:101], v[174:177], v[190:193], v[98:101]
	v_mfma_f32_16x16x32_bf16 v[84:87], v[166:169], v[206:209], v[84:87]
	v_mfma_f32_16x16x32_bf16 v[80:83], v[174:177], v[206:209], v[80:83]
	ds_read_b128 v[242:245], v164 offset:21504
	v_mfma_f32_16x16x32_bf16 v[68:71], v[166:169], v[222:225], v[68:71]
	v_mfma_f32_16x16x32_bf16 v[64:67], v[174:177], v[222:225], v[64:67]
	v_mfma_f32_16x16x32_bf16 v[118:121], v[170:173], v[186:189], v[118:121]
	v_mfma_f32_16x16x32_bf16 v[114:117], v[178:181], v[186:189], v[114:117]
	ds_read_b128 v[246:249], v164 offset:22528
	v_mfma_f32_16x16x32_bf16 v[102:105], v[170:173], v[194:197], v[102:105]
	v_mfma_f32_16x16x32_bf16 v[98:101], v[178:181], v[194:197], v[98:101]
	v_mfma_f32_16x16x32_bf16 v[84:87], v[170:173], v[210:213], v[84:87]
	v_mfma_f32_16x16x32_bf16 v[80:83], v[178:181], v[210:213], v[80:83]
	v_mfma_f32_16x16x32_bf16 v[68:71], v[170:173], v[226:229], v[68:71]
	v_mfma_f32_16x16x32_bf16 v[64:67], v[178:181], v[226:229], v[64:67]
	s_setprio 0
	s_barrier
	s_add_i32 s26, s27, s73
	s_mov_b32 m0, s26
	ds_read_b128 v[226:229], v164 offset:23552
	global_load_lds_dwordx4 v132, s[66:67]
	s_add_i32 m0, s26, 0x2000
	s_add_u32 s26, s66, 0x80000
	s_addc_u32 s27, s67, 0
	s_add_i32 s25, s25, s73
	global_load_lds_dwordx4 v136, s[66:67]
	s_mov_b32 m0, s25
	s_nop 0
	global_load_lds_dwordx4 v132, s[26:27]
	s_add_i32 m0, s25, 0x2000
	s_nop 0
	global_load_lds_dwordx4 v136, s[26:27]
	s_mov_b32 m0, s82
	s_nop 0
	global_load_lds_dwordx4 v130, s[68:69]
	s_mov_b32 m0, s83
	s_nop 0
	global_load_lds_dwordx4 v134, s[68:69]
	s_waitcnt vmcnt(6)
	s_waitcnt lgkmcnt(0)
	s_barrier
; #define PG8_STAGE(bufoff, gbase, voff) do { _Pragma("unroll") for (int _i = 0; _i < 2; ++_i) \
;         __builtin_amdgcn_global_load_lds((const unsigned*)((const char*)(gbase) + (voff)[_i]), (PG8_LAS unsigned*)(lds + (bufoff) + ldsw + _i * 8192), 16, 0, 0); } while (0)
; #define PG8_LDA(dst, b, h) do { _Pragma("unroll") for (int m = 0; m < 4; ++m) _Pragma("unroll") for (int k = 0; k < 2; ++k) dst[m][k] = *(const PG8_LAS bf16x8*)(lds + PG8_SA(b, h) + aoff + m * 2048 + k * 1024); } while (0)
; #define PG8_LDB(dst, b, h) do { _Pragma("unroll") for (int n = 0; n < 2; ++n) _Pragma("unroll") for (int k = 0; k < 2; ++k) dst[n][k] = *(const PG8_LAS bf16x8*)(lds + PG8_SB(b, h) + boff + n * 2048 + k * 1024); } while (0)
; #define PG8_MMA(ai, bj, At, Bt) do { __builtin_amdgcn_s_setprio(1); _Pragma("unroll") for (int m = 0; m < 4; ++m) _Pragma("unroll") for (int n = 0; n < 2; ++n) _Pragma("unroll") for (int k = 0; k < 2; ++k) \
;         acc[ai][bj][m][n] = __builtin_amdgcn_mfma_f32_16x16x32_bf16(Bt[n][k], At[m][k], acc[ai][bj][m][n], 0, 0, 0); __builtin_amdgcn_s_setprio(0); } while (0)
; #define PG8_WAIT_V(n) asm volatile("s_waitcnt vmcnt(" #n ")" ::: "memory")
; #define PG8_WAIT_L(n) asm volatile("s_waitcnt lgkmcnt(" #n ")" ::: "memory")
; #define PG8_BAR __builtin_amdgcn_s_barrier()
; #define PG8_SCHED __builtin_amdgcn_sched_barrier(0)
; template <class Epi, class Sched, bool ALIGN_EPI = true, bool SP2 = true>
; __device__ __forceinline__ void gemm_phase(PG8_LAS unsigned char* lds, const Gemm g, const Sched& S, const Epi& E, const int tid) {
;     ...
;             PG8_WAIT_V(8); PG8_WAIT_L(0); PG8_BAR; PG8_MMA(1, 0, At, B0); PG8_MMA(1, 1, At, B1); PG8_BAR; PG8_SCHED;
;             PG8_LDB(B0, 1, 0); PG8_LDB(B1, 1, 1); PG8_SCHED; PG8_LDA(At, 1, 0); PG8_STAGE(PG8_SA(0, 1), a2 + hstepA, voffA);
;             PG8_WAIT_V(8); PG8_WAIT_L(0); PG8_BAR; PG8_MMA(0, 0, At, B0); PG8_MMA(0, 1, At, B1); PG8_BAR; PG8_SCHED;
	s_setprio 1
	s_waitcnt lgkmcnt(0)
	v_mfma_f32_16x16x32_bf16 v[60:63], v[146:149], v[200:203], v[60:63]
	v_mfma_f32_16x16x32_bf16 v[56:59], v[154:157], v[200:203], v[56:59]
	ds_read_b128 v[182:185], v164 offset:32768
	v_mfma_f32_16x16x32_bf16 v[44:47], v[146:149], v[230:233], v[44:47]
	v_mfma_f32_16x16x32_bf16 v[40:43], v[154:157], v[230:233], v[40:43]
	v_mfma_f32_16x16x32_bf16 v[28:31], v[146:149], v[238:241], v[28:31]
	v_mfma_f32_16x16x32_bf16 v[24:27], v[154:157], v[238:241], v[24:27]
	ds_read_b128 v[186:189], v164 offset:33792
	v_mfma_f32_16x16x32_bf16 v[12:15], v[146:149], v[246:249], v[12:15]
	v_mfma_f32_16x16x32_bf16 v[8:11], v[154:157], v[246:249], v[8:11]
	v_mfma_f32_16x16x32_bf16 v[60:63], v[150:153], v[218:221], v[60:63]
	v_mfma_f32_16x16x32_bf16 v[56:59], v[158:161], v[218:221], v[56:59]
	ds_read_b128 v[190:193], v164 offset:34816
	v_mfma_f32_16x16x32_bf16 v[44:47], v[150:153], v[234:237], v[44:47]
	v_mfma_f32_16x16x32_bf16 v[40:43], v[158:161], v[234:237], v[40:43]
	v_mfma_f32_16x16x32_bf16 v[28:31], v[150:153], v[242:245], v[28:31]
	v_mfma_f32_16x16x32_bf16 v[24:27], v[158:161], v[242:245], v[24:27]
	ds_read_b128 v[194:197], v164 offset:35840
	v_mfma_f32_16x16x32_bf16 v[12:15], v[150:153], v[226:229], v[12:15]
	v_mfma_f32_16x16x32_bf16 v[8:11], v[158:161], v[226:229], v[8:11]
	s_setprio 0
	s_setprio 1
	v_mfma_f32_16x16x32_bf16 v[52:55], v[166:169], v[200:203], v[52:55]
	v_mfma_f32_16x16x32_bf16 v[48:51], v[174:177], v[200:203], v[48:51]
	ds_read_b128 v[206:209], v164 offset:36864
	v_mfma_f32_16x16x32_bf16 v[36:39], v[166:169], v[230:233], v[36:39]
	v_mfma_f32_16x16x32_bf16 v[32:35], v[174:177], v[230:233], v[32:35]
	v_mfma_f32_16x16x32_bf16 v[20:23], v[166:169], v[238:241], v[20:23]
	v_mfma_f32_16x16x32_bf16 v[16:19], v[174:177], v[238:241], v[16:19]
	ds_read_b128 v[210:213], v164 offset:37888
	v_mfma_f32_16x16x32_bf16 v[4:7], v[166:169], v[246:249], v[4:7]
	v_mfma_f32_16x16x32_bf16 v[0:3], v[174:177], v[246:249], v[0:3]
	v_mfma_f32_16x16x32_bf16 v[52:55], v[170:173], v[218:221], v[52:55]
	v_mfma_f32_16x16x32_bf16 v[48:51], v[178:181], v[218:221], v[48:51]
	ds_read_b128 v[222:225], v164 offset:38912
	v_mfma_f32_16x16x32_bf16 v[36:39], v[170:173], v[234:237], v[36:39]
	v_mfma_f32_16x16x32_bf16 v[32:35], v[178:181], v[234:237], v[32:35]
	v_mfma_f32_16x16x32_bf16 v[20:23], v[170:173], v[242:245], v[20:23]
	v_mfma_f32_16x16x32_bf16 v[16:19], v[178:181], v[242:245], v[16:19]
	v_mfma_f32_16x16x32_bf16 v[4:7], v[170:173], v[226:229], v[4:7]
	v_mfma_f32_16x16x32_bf16 v[0:3], v[178:181], v[226:229], v[0:3]
	s_setprio 0
	s_barrier
	s_add_i32 s25, 0, 0x18000
	s_add_i32 s28, 0, 0x1c000
	v_add_u32_e32 v158, s25, v163
	v_add_u32_e32 v165, s28, v163
	ds_read_b128 v[146:149], v158
	ds_read_b128 v[150:153], v158 offset:1024
	ds_read_b128 v[154:157], v158 offset:2048
	ds_read_b128 v[158:161], v158 offset:3072
	ds_read_b128 v[166:169], v165
	ds_read_b128 v[170:173], v165 offset:1024
	ds_read_b128 v[174:177], v165 offset:2048
	ds_read_b128 v[178:181], v165 offset:3072
	s_add_u32 s26, s68, 0x80000
	s_addc_u32 s27, s69, 0
	s_mov_b32 m0, s84
	ds_read_b128 v[226:229], v164 offset:39936
	global_load_lds_dwordx4 v130, s[26:27]
	s_mov_b32 m0, s85
	s_nop 0
	global_load_lds_dwordx4 v134, s[26:27]
	s_waitcnt vmcnt(8)
	s_waitcnt lgkmcnt(0)
	s_barrier
	s_setprio 1
	s_waitcnt lgkmcnt(0)
	v_mfma_f32_16x16x32_bf16 v[126:129], v[146:149], v[182:185], v[126:129]
	v_mfma_f32_16x16x32_bf16 v[122:125], v[154:157], v[182:185], v[122:125]
	ds_read_b128 v[200:203], v164 offset:49152
	v_mfma_f32_16x16x32_bf16 v[110:113], v[146:149], v[190:193], v[110:113]
	v_mfma_f32_16x16x32_bf16 v[106:109], v[154:157], v[190:193], v[106:109]
	v_mfma_f32_16x16x32_bf16 v[92:95], v[146:149], v[206:209], v[92:95]
	v_mfma_f32_16x16x32_bf16 v[88:91], v[154:157], v[206:209], v[88:91]
	ds_read_b128 v[218:221], v164 offset:50176
	v_mfma_f32_16x16x32_bf16 v[76:79], v[146:149], v[222:225], v[76:79]
	v_mfma_f32_16x16x32_bf16 v[72:75], v[154:157], v[222:225], v[72:75]
	v_mfma_f32_16x16x32_bf16 v[126:129], v[150:153], v[186:189], v[126:129]
	v_mfma_f32_16x16x32_bf16 v[122:125], v[158:161], v[186:189], v[122:125]
	ds_read_b128 v[230:233], v164 offset:51200
	v_mfma_f32_16x16x32_bf16 v[110:113], v[150:153], v[194:197], v[110:113]
	v_mfma_f32_16x16x32_bf16 v[106:109], v[158:161], v[194:197], v[106:109]
	v_mfma_f32_16x16x32_bf16 v[92:95], v[150:153], v[210:213], v[92:95]
	v_mfma_f32_16x16x32_bf16 v[88:91], v[158:161], v[210:213], v[88:91]
	ds_read_b128 v[234:237], v164 offset:52224
	v_mfma_f32_16x16x32_bf16 v[76:79], v[150:153], v[226:229], v[76:79]
	v_mfma_f32_16x16x32_bf16 v[72:75], v[158:161], v[226:229], v[72:75]
	s_setprio 0
	s_setprio 1
	v_mfma_f32_16x16x32_bf16 v[118:121], v[166:169], v[182:185], v[118:121]
	v_mfma_f32_16x16x32_bf16 v[114:117], v[174:177], v[182:185], v[114:117]
	ds_read_b128 v[238:241], v164 offset:53248
	v_mfma_f32_16x16x32_bf16 v[102:105], v[166:169], v[190:193], v[102:105]
	v_mfma_f32_16x16x32_bf16 v[98:101], v[174:177], v[190:193], v[98:101]
	v_mfma_f32_16x16x32_bf16 v[84:87], v[166:169], v[206:209], v[84:87]
	v_mfma_f32_16x16x32_bf16 v[80:83], v[174:177], v[206:209], v[80:83]
	ds_read_b128 v[242:245], v164 offset:54272
	v_mfma_f32_16x16x32_bf16 v[68:71], v[166:169], v[222:225], v[68:71]
	v_mfma_f32_16x16x32_bf16 v[64:67], v[174:177], v[222:225], v[64:67]
	v_mfma_f32_16x16x32_bf16 v[118:121], v[170:173], v[186:189], v[118:121]
	v_mfma_f32_16x16x32_bf16 v[114:117], v[178:181], v[186:189], v[114:117]
	ds_read_b128 v[246:249], v164 offset:55296
	v_mfma_f32_16x16x32_bf16 v[102:105], v[170:173], v[194:197], v[102:105]
	v_mfma_f32_16x16x32_bf16 v[98:101], v[178:181], v[194:197], v[98:101]
	v_mfma_f32_16x16x32_bf16 v[84:87], v[170:173], v[210:213], v[84:87]
	v_mfma_f32_16x16x32_bf16 v[80:83], v[178:181], v[210:213], v[80:83]
	v_mfma_f32_16x16x32_bf16 v[68:71], v[170:173], v[226:229], v[68:71]
	v_mfma_f32_16x16x32_bf16 v[64:67], v[178:181], v[226:229], v[64:67]
	s_setprio 0
	s_barrier
; #define PG8_STAGE(bufoff, gbase, voff) do { _Pragma("unroll") for (int _i = 0; _i < 2; ++_i) \
;         __builtin_amdgcn_global_load_lds((const unsigned*)((const char*)(gbase) + (voff)[_i]), (PG8_LAS unsigned*)(lds + (bufoff) + ldsw + _i * 8192), 16, 0, 0); } while (0)
; #define PG8_LDA(dst, b, h) do { _Pragma("unroll") for (int m = 0; m < 4; ++m) _Pragma("unroll") for (int k = 0; k < 2; ++k) dst[m][k] = *(const PG8_LAS bf16x8*)(lds + PG8_SA(b, h) + aoff + m * 2048 + k * 1024); } while (0)
; #define PG8_MMA(ai, bj, At, Bt) do { __builtin_amdgcn_s_setprio(1); _Pragma("unroll") for (int m = 0; m < 4; ++m) _Pragma("unroll") for (int n = 0; n < 2; ++n) _Pragma("unroll") for (int k = 0; k < 2; ++k) \
;         acc[ai][bj][m][n] = __builtin_amdgcn_mfma_f32_16x16x32_bf16(Bt[n][k], At[m][k], acc[ai][bj][m][n], 0, 0, 0); __builtin_amdgcn_s_setprio(0); } while (0)
; #define PG8_WAIT_V(n) asm volatile("s_waitcnt vmcnt(" #n ")" ::: "memory")
; #define PG8_WAIT_L(n) asm volatile("s_waitcnt lgkmcnt(" #n ")" ::: "memory")
; #define PG8_BAR __builtin_amdgcn_s_barrier()
; #define PG8_SCHED __builtin_amdgcn_sched_barrier(0)
; template <class Epi, class Sched, bool ALIGN_EPI = true, bool SP2 = true>
; __device__ __forceinline__ void gemm_phase(PG8_LAS unsigned char* lds, const Gemm g, const Sched& S, const Epi& E, const int tid) {
;     ...
;             PG8_LDA(At, 1, 1); PG8_STAGE(PG8_SB(1, 0), b3, voffB); PG8_STAGE(PG8_SB(1, 1), b3 + hstepB, voffB); PG8_STAGE(PG8_SA(1, 0), a3, voffA);
;             PG8_WAIT_V(8); PG8_WAIT_L(0); PG8_BAR; PG8_MMA(1, 0, At, B0); PG8_MMA(1, 1, At, B1); PG8_BAR; PG8_SCHED;
	s_add_u32 s4, s68, 0x80
	s_addc_u32 s5, s69, 0
	s_mov_b32 m0, s88
	s_nop 0
	global_load_lds_dwordx4 v130, s[4:5]
	s_mov_b32 m0, s89
	s_nop 0
	global_load_lds_dwordx4 v134, s[4:5]
	s_add_i32 s25, s25, s73
	s_add_u32 s4, s66, 0x80
	s_addc_u32 s5, s67, 0
	s_mov_b32 m0, s25
	ds_read_b128 v[226:229], v164 offset:56320
	global_load_lds_dwordx4 v132, s[4:5]
	s_add_i32 m0, s25, 0x2000
	s_add_u32 s26, s66, 0x80080
	s_addc_u32 s27, s67, 0
	s_add_i32 s25, s28, s73
	global_load_lds_dwordx4 v136, s[4:5]
	s_mov_b32 m0, s25
	s_nop 0
	global_load_lds_dwordx4 v132, s[26:27]
	s_add_i32 m0, s25, 0x2000
	s_nop 0
	global_load_lds_dwordx4 v136, s[26:27]
	s_waitcnt vmcnt(6)
	s_waitcnt lgkmcnt(0)
	s_barrier
	s_setprio 1
	s_waitcnt lgkmcnt(0)
	v_mfma_f32_16x16x32_bf16 v[60:63], v[146:149], v[200:203], v[60:63]
	v_mfma_f32_16x16x32_bf16 v[56:59], v[154:157], v[200:203], v[56:59]
	v_mfma_f32_16x16x32_bf16 v[44:47], v[146:149], v[230:233], v[44:47]
	v_mfma_f32_16x16x32_bf16 v[40:43], v[154:157], v[230:233], v[40:43]
	v_mfma_f32_16x16x32_bf16 v[28:31], v[146:149], v[238:241], v[28:31]
	v_mfma_f32_16x16x32_bf16 v[24:27], v[154:157], v[238:241], v[24:27]
	v_mfma_f32_16x16x32_bf16 v[12:15], v[146:149], v[246:249], v[12:15]
	v_mfma_f32_16x16x32_bf16 v[8:11], v[154:157], v[246:249], v[8:11]
	v_mfma_f32_16x16x32_bf16 v[60:63], v[150:153], v[218:221], v[60:63]
	v_mfma_f32_16x16x32_bf16 v[56:59], v[158:161], v[218:221], v[56:59]
	v_mfma_f32_16x16x32_bf16 v[44:47], v[150:153], v[234:237], v[44:47]
	v_mfma_f32_16x16x32_bf16 v[40:43], v[158:161], v[234:237], v[40:43]
	v_mfma_f32_16x16x32_bf16 v[28:31], v[150:153], v[242:245], v[28:31]
	v_mfma_f32_16x16x32_bf16 v[24:27], v[158:161], v[242:245], v[24:27]
	v_mfma_f32_16x16x32_bf16 v[12:15], v[150:153], v[226:229], v[12:15]
	v_mfma_f32_16x16x32_bf16 v[8:11], v[158:161], v[226:229], v[8:11]
	s_setprio 0
	s_setprio 1
	v_mfma_f32_16x16x32_bf16 v[52:55], v[166:169], v[200:203], v[52:55]
	v_mfma_f32_16x16x32_bf16 v[48:51], v[174:177], v[200:203], v[48:51]
	v_mfma_f32_16x16x32_bf16 v[36:39], v[166:169], v[230:233], v[36:39]
	v_mfma_f32_16x16x32_bf16 v[32:35], v[174:177], v[230:233], v[32:35]
	v_mfma_f32_16x16x32_bf16 v[20:23], v[166:169], v[238:241], v[20:23]
	v_mfma_f32_16x16x32_bf16 v[16:19], v[174:177], v[238:241], v[16:19]
	v_mfma_f32_16x16x32_bf16 v[4:7], v[166:169], v[246:249], v[4:7]
	v_mfma_f32_16x16x32_bf16 v[0:3], v[174:177], v[246:249], v[0:3]
	v_mfma_f32_16x16x32_bf16 v[52:55], v[170:173], v[218:221], v[52:55]
	v_mfma_f32_16x16x32_bf16 v[48:51], v[178:181], v[218:221], v[48:51]
	v_mfma_f32_16x16x32_bf16 v[36:39], v[170:173], v[234:237], v[36:39]
	v_mfma_f32_16x16x32_bf16 v[32:35], v[178:181], v[234:237], v[32:35]
	v_mfma_f32_16x16x32_bf16 v[20:23], v[170:173], v[242:245], v[20:23]
	v_mfma_f32_16x16x32_bf16 v[16:19], v[178:181], v[242:245], v[16:19]
	v_mfma_f32_16x16x32_bf16 v[4:7], v[170:173], v[226:229], v[4:7]
	v_mfma_f32_16x16x32_bf16 v[0:3], v[178:181], v[226:229], v[0:3]
	s_setprio 0
	s_barrier
	s_add_i32 s24, s24, 2
	s_add_u32 s62, s62, 0x100
	s_addc_u32 s63, s63, 0
	s_add_u32 s22, s22, 0x100
	s_addc_u32 s23, s23, 0
	s_cmp_gt_u32 s24, 29
	s_cbranch_scc0 .LBB0_381
	v_mov_b32_e32 v218, 0x2a00
	v_mov_b32_e32 v219, 0xf149f2ca
	v_mov_b32_e32 v220, 0xe00
	s_mov_b64 s[4:5], 0x80
	s_and_b64 vcc, exec, s[52:53]
	s_cbranch_vccz .LBB0_384
	s_barrier

; #define PG8_STAGE(bufoff, gbase, voff) do { _Pragma("unroll") for (int _i = 0; _i < 2; ++_i) \
;         __builtin_amdgcn_global_load_lds((const unsigned*)((const char*)(gbase) + (voff)[_i]), (PG8_LAS unsigned*)(lds + (bufoff) + ldsw + _i * 8192), 16, 0, 0); } while (0)
; #define PG8_LDA(dst, b, h) do { _Pragma("unroll") for (int m = 0; m < 4; ++m) _Pragma("unroll") for (int k = 0; k < 2; ++k) dst[m][k] = *(const PG8_LAS bf16x8*)(lds + PG8_SA(b, h) + aoff + m * 2048 + k * 1024); } while (0)
; #define PG8_LDB(dst, b, h) do { _Pragma("unroll") for (int n = 0; n < 2; ++n) _Pragma("unroll") for (int k = 0; k < 2; ++k) dst[n][k] = *(const PG8_LAS bf16x8*)(lds + PG8_SB(b, h) + boff + n * 2048 + k * 1024); } while (0)
; #define PG8_MMA(ai, bj, At, Bt) do { __builtin_amdgcn_s_setprio(1); _Pragma("unroll") for (int m = 0; m < 4; ++m) _Pragma("unroll") for (int n = 0; n < 2; ++n) _Pragma("unroll") for (int k = 0; k < 2; ++k) \
;         acc[ai][bj][m][n] = __builtin_amdgcn_mfma_f32_16x16x32_bf16(Bt[n][k], At[m][k], acc[ai][bj][m][n], 0, 0, 0); __builtin_amdgcn_s_setprio(0); } while (0)
; #define PG8_WAIT_V(n) asm volatile("s_waitcnt vmcnt(" #n ")" ::: "memory")
; #define PG8_BAR __builtin_amdgcn_s_barrier()
; template <class Epi, class Sched, bool ALIGN_EPI = true, bool SP2 = true>
; __device__ __forceinline__ void gemm_phase(PG8_LAS unsigned char* lds, const Gemm g, const Sched& S, const Epi& E, const int tid) {
;     ...
;         for (int t = 0; t < nt; t += 2) {
;             const bool last = (t == nt - 2);
;             const char* a1 = cA + (size_t)(t + 1) * kstep;
;             const char* a2 = last ? nA : cA + (size_t)(t + 2) * kstep; const char* b2 = last ? nB : cB + (size_t)(t + 2) * kstep;
;             const char* a3 = a2 + kstep; const char* b3 = b2 + kstep;
;             if (last && has_next) S.a_ready(nxt);
;             if constexpr (SP2) {
;             PG8_LDB(B0, 0, 0); PG8_LDB(B1, 0, 1); PG8_SCHED; PG8_LDA(At, 0, 0); PG8_STAGE(PG8_SA(1, 1), a1 + hstepA, voffA);
;             PG8_WAIT_V(8); PG8_WAIT_L(0); PG8_BAR; PG8_MMA(0, 0, At, B0); PG8_MMA(0, 1, At, B1); PG8_BAR; PG8_SCHED;
;             PG8_LDA(At, 0, 1); PG8_STAGE(PG8_SB(0, 0), b2, voffB); PG8_STAGE(PG8_SB(0, 1), b2 + hstepB, voffB); PG8_STAGE(PG8_SA(0, 0), a2, voffA);
;             PG8_WAIT_V(8); PG8_WAIT_L(0); PG8_BAR; PG8_MMA(1, 0, At, B0); PG8_MMA(1, 1, At, B1); PG8_BAR; PG8_SCHED;
.LBB0_1077:
	s_add_i32 s63, s82, 2
	s_add_u32 s83, s80, 0xfff80080
	s_addc_u32 s84, s81, -1
	s_add_i32 vcc_lo, 0, 0x10000
	s_cmp_eq_u32 s29, s82
	s_cselect_b32 s85, s67, s84
	s_cselect_b32 s84, s66, s83
	v_add_u32_e32 v96, vcc_lo, v141
	s_cselect_b32 s83, s69, s61
	s_cselect_b32 s82, s68, s59
	s_add_i32 s30, 0, 0x14000
	ds_read_b128 v[146:149], v96
	ds_read_b128 v[150:153], v96 offset:1024
	ds_read_b128 v[154:157], v96 offset:2048
	ds_read_b128 v[158:161], v96 offset:3072
	v_add_u32_e32 v96, s30, v141
	ds_read_b128 v[162:165], v96
	ds_read_b128 v[166:169], v96 offset:1024
	ds_read_b128 v[170:173], v96 offset:2048
	ds_read_b128 v[174:177], v96 offset:3072
	s_add_i32 m0, s25, 0xc000
	ds_read_b128 v[178:181], v145
	ds_read_b128 v[182:185], v145 offset:1024
	ds_read_b128 v[186:189], v145 offset:2048
	ds_read_b128 v[190:193], v145 offset:3072
	ds_read_b128 v[194:197], v145 offset:4096
	ds_read_b128 v[200:203], v145 offset:5120
	ds_read_b128 v[206:209], v145 offset:6144
	ds_read_b128 v[210:213], v145 offset:7168
	global_load_lds_dwordx4 v136, s[80:81]
	s_add_i32 m0, s25, 0xe000
	s_nop 0
	global_load_lds_dwordx4 v138, s[80:81]
	s_waitcnt vmcnt(4)
	s_waitcnt lgkmcnt(0)
	s_barrier
	s_setprio 1
	s_waitcnt lgkmcnt(0)
	v_mfma_f32_16x16x32_bf16 v[92:95], v[146:149], v[178:181], v[92:95]
	v_mfma_f32_16x16x32_bf16 v[130:133], v[154:157], v[178:181], v[130:133]
	ds_read_b128 v[224:227], v145 offset:16384
	v_mfma_f32_16x16x32_bf16 v[126:129], v[146:149], v[186:189], v[126:129]
	v_mfma_f32_16x16x32_bf16 v[122:125], v[154:157], v[186:189], v[122:125]
	v_mfma_f32_16x16x32_bf16 v[118:121], v[146:149], v[194:197], v[118:121]
	v_mfma_f32_16x16x32_bf16 v[110:113], v[154:157], v[194:197], v[110:113]
	ds_read_b128 v[228:231], v145 offset:17408
	v_mfma_f32_16x16x32_bf16 v[76:79], v[146:149], v[206:209], v[76:79]
	v_mfma_f32_16x16x32_bf16 v[72:75], v[154:157], v[206:209], v[72:75]
	v_mfma_f32_16x16x32_bf16 v[92:95], v[150:153], v[182:185], v[92:95]
	v_mfma_f32_16x16x32_bf16 v[130:133], v[158:161], v[182:185], v[130:133]
	ds_read_b128 v[232:235], v145 offset:18432
	v_mfma_f32_16x16x32_bf16 v[126:129], v[150:153], v[190:193], v[126:129]
	v_mfma_f32_16x16x32_bf16 v[122:125], v[158:161], v[190:193], v[122:125]
	v_mfma_f32_16x16x32_bf16 v[118:121], v[150:153], v[200:203], v[118:121]
	v_mfma_f32_16x16x32_bf16 v[110:113], v[158:161], v[200:203], v[110:113]
	ds_read_b128 v[236:239], v145 offset:19456
	v_mfma_f32_16x16x32_bf16 v[76:79], v[150:153], v[210:213], v[76:79]
	v_mfma_f32_16x16x32_bf16 v[72:75], v[158:161], v[210:213], v[72:75]
	s_setprio 0
	s_setprio 1
	v_mfma_f32_16x16x32_bf16 v[88:91], v[162:165], v[178:181], v[88:91]
	v_mfma_f32_16x16x32_bf16 v[84:87], v[170:173], v[178:181], v[84:87]
	ds_read_b128 v[240:243], v145 offset:20480
	v_mfma_f32_16x16x32_bf16 v[114:117], v[162:165], v[186:189], v[114:117]
	v_mfma_f32_16x16x32_bf16 v[106:109], v[170:173], v[186:189], v[106:109]
	v_mfma_f32_16x16x32_bf16 v[102:105], v[162:165], v[194:197], v[102:105]
	v_mfma_f32_16x16x32_bf16 v[80:83], v[170:173], v[194:197], v[80:83]
	ds_read_b128 v[244:247], v145 offset:21504
	v_mfma_f32_16x16x32_bf16 v[68:71], v[162:165], v[206:209], v[68:71]
	v_mfma_f32_16x16x32_bf16 v[64:67], v[170:173], v[206:209], v[64:67]
	v_mfma_f32_16x16x32_bf16 v[88:91], v[166:169], v[182:185], v[88:91]
	v_mfma_f32_16x16x32_bf16 v[84:87], v[174:177], v[182:185], v[84:87]
	ds_read_b128 v[248:251], v145 offset:22528
	v_mfma_f32_16x16x32_bf16 v[114:117], v[166:169], v[190:193], v[114:117]
	v_mfma_f32_16x16x32_bf16 v[106:109], v[174:177], v[190:193], v[106:109]
	v_mfma_f32_16x16x32_bf16 v[102:105], v[166:169], v[200:203], v[102:105]
	v_mfma_f32_16x16x32_bf16 v[80:83], v[174:177], v[200:203], v[80:83]
	v_mfma_f32_16x16x32_bf16 v[68:71], v[166:169], v[210:213], v[68:71]
	v_mfma_f32_16x16x32_bf16 v[64:67], v[174:177], v[210:213], v[64:67]
	s_setprio 0
	s_barrier
	s_add_i32 s31, vcc_lo, s24
	s_mov_b32 m0, s31
	ds_read_b128 v[210:213], v145 offset:23552
	global_load_lds_dwordx4 v100, s[82:83]
	s_add_i32 m0, s31, 0x2000
	s_add_u32 vcc_lo, s82, 0x80000
	s_addc_u32 vcc_hi, s83, 0
	s_add_i32 s30, s30, s24
	global_load_lds_dwordx4 v134, s[82:83]
	s_mov_b32 m0, s30
	s_nop 0
	global_load_lds_dwordx4 v100, vcc
	s_add_i32 m0, s30, 0x2000
	s_nop 0
	global_load_lds_dwordx4 v134, vcc
	s_mov_b32 m0, s25
	s_nop 0
	global_load_lds_dwordx4 v100, s[84:85]
	s_mov_b32 m0, s49
	s_nop 0
	global_load_lds_dwordx4 v134, s[84:85]
	s_waitcnt vmcnt(6)
	s_waitcnt lgkmcnt(0)
	s_barrier
; #define PG8_STAGE(bufoff, gbase, voff) do { _Pragma("unroll") for (int _i = 0; _i < 2; ++_i) \
;         __builtin_amdgcn_global_load_lds((const unsigned*)((const char*)(gbase) + (voff)[_i]), (PG8_LAS unsigned*)(lds + (bufoff) + ldsw + _i * 8192), 16, 0, 0); } while (0)
; #define PG8_LDA(dst, b, h) do { _Pragma("unroll") for (int m = 0; m < 4; ++m) _Pragma("unroll") for (int k = 0; k < 2; ++k) dst[m][k] = *(const PG8_LAS bf16x8*)(lds + PG8_SA(b, h) + aoff + m * 2048 + k * 1024); } while (0)
; #define PG8_LDB(dst, b, h) do { _Pragma("unroll") for (int n = 0; n < 2; ++n) _Pragma("unroll") for (int k = 0; k < 2; ++k) dst[n][k] = *(const PG8_LAS bf16x8*)(lds + PG8_SB(b, h) + boff + n * 2048 + k * 1024); } while (0)
; #define PG8_MMA(ai, bj, At, Bt) do { __builtin_amdgcn_s_setprio(1); _Pragma("unroll") for (int m = 0; m < 4; ++m) _Pragma("unroll") for (int n = 0; n < 2; ++n) _Pragma("unroll") for (int k = 0; k < 2; ++k) \
;         acc[ai][bj][m][n] = __builtin_amdgcn_mfma_f32_16x16x32_bf16(Bt[n][k], At[m][k], acc[ai][bj][m][n], 0, 0, 0); __builtin_amdgcn_s_setprio(0); } while (0)
; #define PG8_WAIT_V(n) asm volatile("s_waitcnt vmcnt(" #n ")" ::: "memory")
; #define PG8_WAIT_L(n) asm volatile("s_waitcnt lgkmcnt(" #n ")" ::: "memory")
; #define PG8_BAR __builtin_amdgcn_s_barrier()
; #define PG8_SCHED __builtin_amdgcn_sched_barrier(0)
; template <class Epi, class Sched, bool ALIGN_EPI = true, bool SP2 = true>
; __device__ __forceinline__ void gemm_phase(PG8_LAS unsigned char* lds, const Gemm g, const Sched& S, const Epi& E, const int tid) {
;     ...
;             PG8_WAIT_V(8); PG8_WAIT_L(0); PG8_BAR; PG8_MMA(1, 0, At, B0); PG8_MMA(1, 1, At, B1); PG8_BAR; PG8_SCHED;
;             PG8_LDB(B0, 1, 0); PG8_LDB(B1, 1, 1); PG8_SCHED; PG8_LDA(At, 1, 0); PG8_STAGE(PG8_SA(0, 1), a2 + hstepA, voffA);
	s_setprio 1
	s_waitcnt lgkmcnt(0)
	v_mfma_f32_16x16x32_bf16 v[56:59], v[146:149], v[224:227], v[56:59]
	v_mfma_f32_16x16x32_bf16 v[60:63], v[154:157], v[224:227], v[60:63]
	ds_read_b128 v[178:181], v145 offset:32768
	v_mfma_f32_16x16x32_bf16 v[44:47], v[146:149], v[232:235], v[44:47]
	v_mfma_f32_16x16x32_bf16 v[40:43], v[154:157], v[232:235], v[40:43]
	v_mfma_f32_16x16x32_bf16 v[28:31], v[146:149], v[240:243], v[28:31]
	v_mfma_f32_16x16x32_bf16 v[24:27], v[154:157], v[240:243], v[24:27]
	ds_read_b128 v[182:185], v145 offset:33792
	v_mfma_f32_16x16x32_bf16 v[12:15], v[146:149], v[248:251], v[12:15]
	v_mfma_f32_16x16x32_bf16 v[8:11], v[154:157], v[248:251], v[8:11]
	v_mfma_f32_16x16x32_bf16 v[56:59], v[150:153], v[228:231], v[56:59]
	v_mfma_f32_16x16x32_bf16 v[60:63], v[158:161], v[228:231], v[60:63]
	ds_read_b128 v[186:189], v145 offset:34816
	v_mfma_f32_16x16x32_bf16 v[44:47], v[150:153], v[236:239], v[44:47]
	v_mfma_f32_16x16x32_bf16 v[40:43], v[158:161], v[236:239], v[40:43]
	v_mfma_f32_16x16x32_bf16 v[28:31], v[150:153], v[244:247], v[28:31]
	v_mfma_f32_16x16x32_bf16 v[24:27], v[158:161], v[244:247], v[24:27]
	ds_read_b128 v[190:193], v145 offset:35840
	v_mfma_f32_16x16x32_bf16 v[12:15], v[150:153], v[210:213], v[12:15]
	v_mfma_f32_16x16x32_bf16 v[8:11], v[158:161], v[210:213], v[8:11]
	s_setprio 0
	s_setprio 1
	v_mfma_f32_16x16x32_bf16 v[52:55], v[162:165], v[224:227], v[52:55]
	v_mfma_f32_16x16x32_bf16 v[48:51], v[170:173], v[224:227], v[48:51]
	ds_read_b128 v[194:197], v145 offset:36864
	v_mfma_f32_16x16x32_bf16 v[36:39], v[162:165], v[232:235], v[36:39]
	v_mfma_f32_16x16x32_bf16 v[32:35], v[170:173], v[232:235], v[32:35]
	v_mfma_f32_16x16x32_bf16 v[20:23], v[162:165], v[240:243], v[20:23]
	v_mfma_f32_16x16x32_bf16 v[16:19], v[170:173], v[240:243], v[16:19]
	ds_read_b128 v[200:203], v145 offset:37888
	v_mfma_f32_16x16x32_bf16 v[4:7], v[162:165], v[248:251], v[4:7]
	v_mfma_f32_16x16x32_bf16 v[0:3], v[170:173], v[248:251], v[0:3]
	v_mfma_f32_16x16x32_bf16 v[52:55], v[166:169], v[228:231], v[52:55]
	v_mfma_f32_16x16x32_bf16 v[48:51], v[174:177], v[228:231], v[48:51]
	ds_read_b128 v[206:209], v145 offset:38912
	v_mfma_f32_16x16x32_bf16 v[36:39], v[166:169], v[236:239], v[36:39]
	v_mfma_f32_16x16x32_bf16 v[32:35], v[174:177], v[236:239], v[32:35]
	v_mfma_f32_16x16x32_bf16 v[20:23], v[166:169], v[244:247], v[20:23]
	v_mfma_f32_16x16x32_bf16 v[16:19], v[174:177], v[244:247], v[16:19]
	v_mfma_f32_16x16x32_bf16 v[4:7], v[166:169], v[210:213], v[4:7]
	v_mfma_f32_16x16x32_bf16 v[0:3], v[174:177], v[210:213], v[0:3]
	s_setprio 0
	s_barrier
	s_add_i32 s30, 0, 0x18000
	v_add_u32_e32 v96, s30, v141
	s_add_i32 s31, 0, 0x1c000
	ds_read_b128 v[146:149], v96
	ds_read_b128 v[150:153], v96 offset:1024
	ds_read_b128 v[154:157], v96 offset:2048
	ds_read_b128 v[158:161], v96 offset:3072
	v_add_u32_e32 v96, s31, v141
	ds_read_b128 v[162:165], v96
	ds_read_b128 v[166:169], v96 offset:1024
	ds_read_b128 v[170:173], v96 offset:2048
	ds_read_b128 v[174:177], v96 offset:3072
	s_add_u32 s84, s84, 0x80000
	s_addc_u32 s85, s85, 0
	s_mov_b32 m0, s51
	ds_read_b128 v[210:213], v145 offset:39936
	global_load_lds_dwordx4 v100, s[84:85]
	s_mov_b32 m0, s76
	s_nop 0
	global_load_lds_dwordx4 v134, s[84:85]
	s_waitcnt vmcnt(8)
	s_waitcnt lgkmcnt(0)
	s_barrier
; #define PG8_STAGE(bufoff, gbase, voff) do { _Pragma("unroll") for (int _i = 0; _i < 2; ++_i) \
;         __builtin_amdgcn_global_load_lds((const unsigned*)((const char*)(gbase) + (voff)[_i]), (PG8_LAS unsigned*)(lds + (bufoff) + ldsw + _i * 8192), 16, 0, 0); } while (0)
; #define PG8_LDA(dst, b, h) do { _Pragma("unroll") for (int m = 0; m < 4; ++m) _Pragma("unroll") for (int k = 0; k < 2; ++k) dst[m][k] = *(const PG8_LAS bf16x8*)(lds + PG8_SA(b, h) + aoff + m * 2048 + k * 1024); } while (0)
; #define PG8_MMA(ai, bj, At, Bt) do { __builtin_amdgcn_s_setprio(1); _Pragma("unroll") for (int m = 0; m < 4; ++m) _Pragma("unroll") for (int n = 0; n < 2; ++n) _Pragma("unroll") for (int k = 0; k < 2; ++k) \
;         acc[ai][bj][m][n] = __builtin_amdgcn_mfma_f32_16x16x32_bf16(Bt[n][k], At[m][k], acc[ai][bj][m][n], 0, 0, 0); __builtin_amdgcn_s_setprio(0); } while (0)
; #define PG8_WAIT_V(n) asm volatile("s_waitcnt vmcnt(" #n ")" ::: "memory")
; #define PG8_WAIT_L(n) asm volatile("s_waitcnt lgkmcnt(" #n ")" ::: "memory")
; #define PG8_BAR __builtin_amdgcn_s_barrier()
; #define PG8_SCHED __builtin_amdgcn_sched_barrier(0)
; template <class Epi, class Sched, bool ALIGN_EPI = true, bool SP2 = true>
; __device__ __forceinline__ void gemm_phase(PG8_LAS unsigned char* lds, const Gemm g, const Sched& S, const Epi& E, const int tid) {
;     ...
;             PG8_WAIT_V(8); PG8_WAIT_L(0); PG8_BAR; PG8_MMA(0, 0, At, B0); PG8_MMA(0, 1, At, B1); PG8_BAR; PG8_SCHED;
;             PG8_LDA(At, 1, 1); PG8_STAGE(PG8_SB(1, 0), b3, voffB); PG8_STAGE(PG8_SB(1, 1), b3 + hstepB, voffB); PG8_STAGE(PG8_SA(1, 0), a3, voffA);
;             PG8_WAIT_V(8); PG8_WAIT_L(0); PG8_BAR; PG8_MMA(1, 0, At, B0); PG8_MMA(1, 1, At, B1); PG8_BAR; PG8_SCHED;
	s_setprio 1
	s_waitcnt lgkmcnt(0)
	v_mfma_f32_16x16x32_bf16 v[92:95], v[146:149], v[178:181], v[92:95]
	v_mfma_f32_16x16x32_bf16 v[130:133], v[154:157], v[178:181], v[130:133]
	ds_read_b128 v[224:227], v145 offset:49152
	v_mfma_f32_16x16x32_bf16 v[126:129], v[146:149], v[186:189], v[126:129]
	v_mfma_f32_16x16x32_bf16 v[122:125], v[154:157], v[186:189], v[122:125]
	v_mfma_f32_16x16x32_bf16 v[118:121], v[146:149], v[194:197], v[118:121]
	v_mfma_f32_16x16x32_bf16 v[110:113], v[154:157], v[194:197], v[110:113]
	ds_read_b128 v[228:231], v145 offset:50176
	v_mfma_f32_16x16x32_bf16 v[76:79], v[146:149], v[206:209], v[76:79]
	v_mfma_f32_16x16x32_bf16 v[72:75], v[154:157], v[206:209], v[72:75]
	v_mfma_f32_16x16x32_bf16 v[92:95], v[150:153], v[182:185], v[92:95]
	v_mfma_f32_16x16x32_bf16 v[130:133], v[158:161], v[182:185], v[130:133]
	ds_read_b128 v[232:235], v145 offset:51200
	v_mfma_f32_16x16x32_bf16 v[126:129], v[150:153], v[190:193], v[126:129]
	v_mfma_f32_16x16x32_bf16 v[122:125], v[158:161], v[190:193], v[122:125]
	v_mfma_f32_16x16x32_bf16 v[118:121], v[150:153], v[200:203], v[118:121]
	v_mfma_f32_16x16x32_bf16 v[110:113], v[158:161], v[200:203], v[110:113]
	ds_read_b128 v[236:239], v145 offset:52224
	v_mfma_f32_16x16x32_bf16 v[76:79], v[150:153], v[210:213], v[76:79]
	v_mfma_f32_16x16x32_bf16 v[72:75], v[158:161], v[210:213], v[72:75]
	s_setprio 0
	s_setprio 1
	v_mfma_f32_16x16x32_bf16 v[88:91], v[162:165], v[178:181], v[88:91]
	v_mfma_f32_16x16x32_bf16 v[84:87], v[170:173], v[178:181], v[84:87]
	ds_read_b128 v[240:243], v145 offset:53248
	v_mfma_f32_16x16x32_bf16 v[114:117], v[162:165], v[186:189], v[114:117]
	v_mfma_f32_16x16x32_bf16 v[106:109], v[170:173], v[186:189], v[106:109]
	v_mfma_f32_16x16x32_bf16 v[102:105], v[162:165], v[194:197], v[102:105]
	v_mfma_f32_16x16x32_bf16 v[80:83], v[170:173], v[194:197], v[80:83]
	ds_read_b128 v[244:247], v145 offset:54272
	v_mfma_f32_16x16x32_bf16 v[68:71], v[162:165], v[206:209], v[68:71]
	v_mfma_f32_16x16x32_bf16 v[64:67], v[170:173], v[206:209], v[64:67]
	v_mfma_f32_16x16x32_bf16 v[88:91], v[166:169], v[182:185], v[88:91]
	v_mfma_f32_16x16x32_bf16 v[84:87], v[174:177], v[182:185], v[84:87]
	ds_read_b128 v[248:251], v145 offset:55296
	v_mfma_f32_16x16x32_bf16 v[114:117], v[166:169], v[190:193], v[114:117]
	v_mfma_f32_16x16x32_bf16 v[106:109], v[174:177], v[190:193], v[106:109]
	v_mfma_f32_16x16x32_bf16 v[102:105], v[166:169], v[200:203], v[102:105]
	v_mfma_f32_16x16x32_bf16 v[80:83], v[174:177], v[200:203], v[80:83]
	v_mfma_f32_16x16x32_bf16 v[68:71], v[166:169], v[210:213], v[68:71]
	v_mfma_f32_16x16x32_bf16 v[64:67], v[174:177], v[210:213], v[64:67]
	s_setprio 0
	s_barrier
	s_add_u32 s4, s84, 0xfff80080
	s_addc_u32 s5, s85, -1
	s_mov_b32 m0, s90
	s_nop 0
	global_load_lds_dwordx4 v100, s[4:5]
	s_mov_b32 m0, s91
	s_nop 0
	global_load_lds_dwordx4 v134, s[4:5]
	s_add_i32 s30, s30, s24
	s_add_u32 s4, s82, 0x80
	s_addc_u32 s5, s83, 0
	s_mov_b32 m0, s30
	ds_read_b128 v[210:213], v145 offset:56320
	global_load_lds_dwordx4 v100, s[4:5]
	s_add_i32 m0, s30, 0x2000
	s_add_u32 s82, s82, 0x80080
	s_addc_u32 s83, s83, 0
	s_add_i32 s30, s31, s24
	global_load_lds_dwordx4 v134, s[4:5]
	s_mov_b32 m0, s30
	s_nop 0
	global_load_lds_dwordx4 v100, s[82:83]
	s_add_i32 m0, s30, 0x2000
	s_nop 0
	global_load_lds_dwordx4 v134, s[82:83]
	s_waitcnt vmcnt(6)
	s_waitcnt lgkmcnt(0)
	s_barrier
	s_setprio 1
	s_waitcnt lgkmcnt(0)
	v_mfma_f32_16x16x32_bf16 v[56:59], v[146:149], v[224:227], v[56:59]
	v_mfma_f32_16x16x32_bf16 v[60:63], v[154:157], v[224:227], v[60:63]
	v_mfma_f32_16x16x32_bf16 v[44:47], v[146:149], v[232:235], v[44:47]
	v_mfma_f32_16x16x32_bf16 v[40:43], v[154:157], v[232:235], v[40:43]
	v_mfma_f32_16x16x32_bf16 v[28:31], v[146:149], v[240:243], v[28:31]
	v_mfma_f32_16x16x32_bf16 v[24:27], v[154:157], v[240:243], v[24:27]
	v_mfma_f32_16x16x32_bf16 v[12:15], v[146:149], v[248:251], v[12:15]
	v_mfma_f32_16x16x32_bf16 v[8:11], v[154:157], v[248:251], v[8:11]
	v_mfma_f32_16x16x32_bf16 v[56:59], v[150:153], v[228:231], v[56:59]
	v_mfma_f32_16x16x32_bf16 v[60:63], v[158:161], v[228:231], v[60:63]
	v_mfma_f32_16x16x32_bf16 v[44:47], v[150:153], v[236:239], v[44:47]
	v_mfma_f32_16x16x32_bf16 v[40:43], v[158:161], v[236:239], v[40:43]
	v_mfma_f32_16x16x32_bf16 v[28:31], v[150:153], v[244:247], v[28:31]
	v_mfma_f32_16x16x32_bf16 v[24:27], v[158:161], v[244:247], v[24:27]
	v_mfma_f32_16x16x32_bf16 v[12:15], v[150:153], v[210:213], v[12:15]
	v_mfma_f32_16x16x32_bf16 v[8:11], v[158:161], v[210:213], v[8:11]
	s_setprio 0
	s_setprio 1
	v_mfma_f32_16x16x32_bf16 v[52:55], v[162:165], v[224:227], v[52:55]
	v_mfma_f32_16x16x32_bf16 v[48:51], v[170:173], v[224:227], v[48:51]
	v_mfma_f32_16x16x32_bf16 v[36:39], v[162:165], v[232:235], v[36:39]
	v_mfma_f32_16x16x32_bf16 v[32:35], v[170:173], v[232:235], v[32:35]
	v_mfma_f32_16x16x32_bf16 v[20:23], v[162:165], v[240:243], v[20:23]
	v_mfma_f32_16x16x32_bf16 v[16:19], v[170:173], v[240:243], v[16:19]
	v_mfma_f32_16x16x32_bf16 v[4:7], v[162:165], v[248:251], v[4:7]
	v_mfma_f32_16x16x32_bf16 v[0:3], v[170:173], v[248:251], v[0:3]
	v_mfma_f32_16x16x32_bf16 v[52:55], v[166:169], v[228:231], v[52:55]
	v_mfma_f32_16x16x32_bf16 v[48:51], v[174:177], v[228:231], v[48:51]
	v_mfma_f32_16x16x32_bf16 v[36:39], v[166:169], v[236:239], v[36:39]
	v_mfma_f32_16x16x32_bf16 v[32:35], v[174:177], v[236:239], v[32:35]
	v_mfma_f32_16x16x32_bf16 v[20:23], v[166:169], v[244:247], v[20:23]
	v_mfma_f32_16x16x32_bf16 v[16:19], v[174:177], v[244:247], v[16:19]
	v_mfma_f32_16x16x32_bf16 v[4:7], v[166:169], v[210:213], v[4:7]
	v_mfma_f32_16x16x32_bf16 v[0:3], v[174:177], v[210:213], v[0:3]
	s_setprio 0
	s_barrier
	s_add_u32 s80, s80, 0x100
	s_addc_u32 s81, s81, 0
	s_add_u32 s59, s59, 0x100
	s_addc_u32 s61, s61, 0
	s_cmp_ge_i32 s63, s57
	s_mov_b32 s82, s63
	s_cbranch_scc0 .LBB0_1077
	s_mov_b64 s[4:5], 0x80

; #define PG8_STAGE(bufoff, gbase, voff) do { _Pragma("unroll") for (int _i = 0; _i < 2; ++_i) \
;         __builtin_amdgcn_global_load_lds((const unsigned*)((const char*)(gbase) + (voff)[_i]), (PG8_LAS unsigned*)(lds + (bufoff) + ldsw + _i * 8192), 16, 0, 0); } while (0)
; #define PG8_LDA(dst, b, h) do { _Pragma("unroll") for (int m = 0; m < 4; ++m) _Pragma("unroll") for (int k = 0; k < 2; ++k) dst[m][k] = *(const PG8_LAS bf16x8*)(lds + PG8_SA(b, h) + aoff + m * 2048 + k * 1024); } while (0)
; #define PG8_LDB(dst, b, h) do { _Pragma("unroll") for (int n = 0; n < 2; ++n) _Pragma("unroll") for (int k = 0; k < 2; ++k) dst[n][k] = *(const PG8_LAS bf16x8*)(lds + PG8_SB(b, h) + boff + n * 2048 + k * 1024); } while (0)
; #define PG8_MMA(ai, bj, At, Bt) do { __builtin_amdgcn_s_setprio(1); _Pragma("unroll") for (int m = 0; m < 4; ++m) _Pragma("unroll") for (int n = 0; n < 2; ++n) _Pragma("unroll") for (int k = 0; k < 2; ++k) \
;         acc[ai][bj][m][n] = __builtin_amdgcn_mfma_f32_16x16x32_bf16(Bt[n][k], At[m][k], acc[ai][bj][m][n], 0, 0, 0); __builtin_amdgcn_s_setprio(0); } while (0)
; #define PG8_WAIT_V(n) asm volatile("s_waitcnt vmcnt(" #n ")" ::: "memory")
; #define PG8_BAR __builtin_amdgcn_s_barrier()
; template <class Epi, class Sched, bool ALIGN_EPI = true, bool SP2 = true>
; __device__ __forceinline__ void gemm_phase(PG8_LAS unsigned char* lds, const Gemm g, const Sched& S, const Epi& E, const int tid) {
;     ...
;         for (int t = 0; t < nt; t += 2) {
;             const bool last = (t == nt - 2);
;             const char* a1 = cA + (size_t)(t + 1) * kstep;
;             const char* a2 = last ? nA : cA + (size_t)(t + 2) * kstep; const char* b2 = last ? nB : cB + (size_t)(t + 2) * kstep;
;             const char* a3 = a2 + kstep; const char* b3 = b2 + kstep;
;             if (last && has_next) S.a_ready(nxt);
;             if constexpr (SP2) {
;             PG8_LDB(B0, 0, 0); PG8_LDB(B1, 0, 1); PG8_SCHED; PG8_LDA(At, 0, 0); PG8_STAGE(PG8_SA(1, 1), a1 + hstepA, voffA);
;             PG8_WAIT_V(8); PG8_WAIT_L(0); PG8_BAR; PG8_MMA(0, 0, At, B0); PG8_MMA(0, 1, At, B1); PG8_BAR; PG8_SCHED;
;             PG8_LDA(At, 0, 1); PG8_STAGE(PG8_SB(0, 0), b2, voffB); PG8_STAGE(PG8_SB(0, 1), b2 + hstepB, voffB); PG8_STAGE(PG8_SA(0, 0), a2, voffA);
;             PG8_WAIT_V(8); PG8_WAIT_L(0); PG8_BAR; PG8_MMA(1, 0, At, B0); PG8_MMA(1, 1, At, B1); PG8_BAR; PG8_SCHED;
.LBB0_1319:
	s_add_u32 s28, s62, 0xfff80080
	s_addc_u32 s29, s63, -1
	s_add_i32 s30, 0, 0x10000
	s_cmp_eq_u32 s52, 28
	s_cselect_b32 s67, s24, s29
	s_cselect_b32 s66, s25, s28
	v_add_u32_e32 v145, s30, v142
	s_cselect_b32 s65, s26, s51
	s_cselect_b32 s64, s27, s49
	s_add_i32 s31, 0, 0x14000
	ds_read_b128 v[146:149], v145
	ds_read_b128 v[150:153], v145 offset:1024
	ds_read_b128 v[154:157], v145 offset:2048
	ds_read_b128 v[158:161], v145 offset:3072
	v_add_u32_e32 v145, s31, v142
	ds_read_b128 v[162:165], v145
	ds_read_b128 v[166:169], v145 offset:1024
	ds_read_b128 v[170:173], v145 offset:2048
	ds_read_b128 v[174:177], v145 offset:3072
	s_add_i32 m0, s22, 0xc000
	ds_read_b128 v[178:181], v144
	ds_read_b128 v[182:185], v144 offset:1024
	ds_read_b128 v[186:189], v144 offset:2048
	ds_read_b128 v[190:193], v144 offset:3072
	ds_read_b128 v[194:197], v144 offset:4096
	ds_read_b128 v[200:203], v144 offset:5120
	ds_read_b128 v[206:209], v144 offset:6144
	ds_read_b128 v[210:213], v144 offset:7168
	global_load_lds_dwordx4 v138, s[62:63]
	s_add_i32 m0, s22, 0xe000
	s_nop 0
	global_load_lds_dwordx4 v140, s[62:63]
	s_waitcnt vmcnt(4)
	s_waitcnt lgkmcnt(0)
	s_barrier
	s_setprio 1
	s_waitcnt lgkmcnt(0)
	v_mfma_f32_16x16x32_bf16 v[126:129], v[146:149], v[178:181], v[126:129]
	v_mfma_f32_16x16x32_bf16 v[118:121], v[154:157], v[178:181], v[118:121]
	ds_read_b128 v[218:221], v144 offset:16384
	v_mfma_f32_16x16x32_bf16 v[110:113], v[146:149], v[186:189], v[110:113]
	v_mfma_f32_16x16x32_bf16 v[102:105], v[154:157], v[186:189], v[102:105]
	v_mfma_f32_16x16x32_bf16 v[92:95], v[146:149], v[194:197], v[92:95]
	v_mfma_f32_16x16x32_bf16 v[84:87], v[154:157], v[194:197], v[84:87]
	ds_read_b128 v[222:225], v144 offset:17408
	v_mfma_f32_16x16x32_bf16 v[76:79], v[146:149], v[206:209], v[76:79]
	v_mfma_f32_16x16x32_bf16 v[68:71], v[154:157], v[206:209], v[68:71]
	v_mfma_f32_16x16x32_bf16 v[126:129], v[150:153], v[182:185], v[126:129]
	v_mfma_f32_16x16x32_bf16 v[118:121], v[158:161], v[182:185], v[118:121]
	ds_read_b128 v[226:229], v144 offset:18432
	v_mfma_f32_16x16x32_bf16 v[110:113], v[150:153], v[190:193], v[110:113]
	v_mfma_f32_16x16x32_bf16 v[102:105], v[158:161], v[190:193], v[102:105]
	v_mfma_f32_16x16x32_bf16 v[92:95], v[150:153], v[200:203], v[92:95]
	v_mfma_f32_16x16x32_bf16 v[84:87], v[158:161], v[200:203], v[84:87]
	ds_read_b128 v[230:233], v144 offset:19456
	v_mfma_f32_16x16x32_bf16 v[76:79], v[150:153], v[210:213], v[76:79]
	v_mfma_f32_16x16x32_bf16 v[68:71], v[158:161], v[210:213], v[68:71]
	s_setprio 0
	s_setprio 1
	v_mfma_f32_16x16x32_bf16 v[122:125], v[162:165], v[178:181], v[122:125]
	v_mfma_f32_16x16x32_bf16 v[114:117], v[170:173], v[178:181], v[114:117]
	ds_read_b128 v[234:237], v144 offset:20480
	v_mfma_f32_16x16x32_bf16 v[106:109], v[162:165], v[186:189], v[106:109]
	v_mfma_f32_16x16x32_bf16 v[98:101], v[170:173], v[186:189], v[98:101]
	v_mfma_f32_16x16x32_bf16 v[88:91], v[162:165], v[194:197], v[88:91]
	v_mfma_f32_16x16x32_bf16 v[80:83], v[170:173], v[194:197], v[80:83]
	ds_read_b128 v[238:241], v144 offset:21504
	v_mfma_f32_16x16x32_bf16 v[72:75], v[162:165], v[206:209], v[72:75]
	v_mfma_f32_16x16x32_bf16 v[64:67], v[170:173], v[206:209], v[64:67]
	v_mfma_f32_16x16x32_bf16 v[122:125], v[166:169], v[182:185], v[122:125]
	v_mfma_f32_16x16x32_bf16 v[114:117], v[174:177], v[182:185], v[114:117]
	ds_read_b128 v[242:245], v144 offset:22528
	v_mfma_f32_16x16x32_bf16 v[106:109], v[166:169], v[190:193], v[106:109]
	v_mfma_f32_16x16x32_bf16 v[98:101], v[174:177], v[190:193], v[98:101]
	v_mfma_f32_16x16x32_bf16 v[88:91], v[166:169], v[200:203], v[88:91]
	v_mfma_f32_16x16x32_bf16 v[80:83], v[174:177], v[200:203], v[80:83]
	ds_read_b128 v[246:249], v144 offset:23552
	v_mfma_f32_16x16x32_bf16 v[72:75], v[166:169], v[210:213], v[72:75]
	v_mfma_f32_16x16x32_bf16 v[64:67], v[174:177], v[210:213], v[64:67]
	s_setprio 0
	s_barrier
	s_add_i32 s28, s30, s21
	s_mov_b32 m0, s28
	s_nop 0
	global_load_lds_dwordx4 v134, s[64:65]
	s_add_i32 m0, s28, 0x2000
	s_add_u32 s28, s64, 0x80000
	s_addc_u32 s29, s65, 0
	s_add_i32 s30, s31, s21
	global_load_lds_dwordx4 v130, s[64:65]
	s_mov_b32 m0, s30
	s_nop 0
	global_load_lds_dwordx4 v134, s[28:29]
	s_add_i32 m0, s30, 0x2000
	s_nop 0
	global_load_lds_dwordx4 v130, s[28:29]
	s_mov_b32 m0, s22
	s_nop 0
	global_load_lds_dwordx4 v136, s[66:67]
	s_mov_b32 m0, s23
	s_nop 0
	global_load_lds_dwordx4 v132, s[66:67]
	s_waitcnt vmcnt(6)
	s_waitcnt lgkmcnt(0)
	s_barrier
; #define PG8_STAGE(bufoff, gbase, voff) do { _Pragma("unroll") for (int _i = 0; _i < 2; ++_i) \
;         __builtin_amdgcn_global_load_lds((const unsigned*)((const char*)(gbase) + (voff)[_i]), (PG8_LAS unsigned*)(lds + (bufoff) + ldsw + _i * 8192), 16, 0, 0); } while (0)
; #define PG8_LDA(dst, b, h) do { _Pragma("unroll") for (int m = 0; m < 4; ++m) _Pragma("unroll") for (int k = 0; k < 2; ++k) dst[m][k] = *(const PG8_LAS bf16x8*)(lds + PG8_SA(b, h) + aoff + m * 2048 + k * 1024); } while (0)
; #define PG8_LDB(dst, b, h) do { _Pragma("unroll") for (int n = 0; n < 2; ++n) _Pragma("unroll") for (int k = 0; k < 2; ++k) dst[n][k] = *(const PG8_LAS bf16x8*)(lds + PG8_SB(b, h) + boff + n * 2048 + k * 1024); } while (0)
; #define PG8_MMA(ai, bj, At, Bt) do { __builtin_amdgcn_s_setprio(1); _Pragma("unroll") for (int m = 0; m < 4; ++m) _Pragma("unroll") for (int n = 0; n < 2; ++n) _Pragma("unroll") for (int k = 0; k < 2; ++k) \
;         acc[ai][bj][m][n] = __builtin_amdgcn_mfma_f32_16x16x32_bf16(Bt[n][k], At[m][k], acc[ai][bj][m][n], 0, 0, 0); __builtin_amdgcn_s_setprio(0); } while (0)
; #define PG8_WAIT_V(n) asm volatile("s_waitcnt vmcnt(" #n ")" ::: "memory")
; #define PG8_WAIT_L(n) asm volatile("s_waitcnt lgkmcnt(" #n ")" ::: "memory")
; #define PG8_BAR __builtin_amdgcn_s_barrier()
; #define PG8_SCHED __builtin_amdgcn_sched_barrier(0)
; template <class Epi, class Sched, bool ALIGN_EPI = true, bool SP2 = true>
; __device__ __forceinline__ void gemm_phase(PG8_LAS unsigned char* lds, const Gemm g, const Sched& S, const Epi& E, const int tid) {
;     ...
;             PG8_WAIT_V(8); PG8_WAIT_L(0); PG8_BAR; PG8_MMA(1, 0, At, B0); PG8_MMA(1, 1, At, B1); PG8_BAR; PG8_SCHED;
;             PG8_LDB(B0, 1, 0); PG8_LDB(B1, 1, 1); PG8_SCHED; PG8_LDA(At, 1, 0); PG8_STAGE(PG8_SA(0, 1), a2 + hstepA, voffA);
	s_setprio 1
	s_waitcnt lgkmcnt(0)
	v_mfma_f32_16x16x32_bf16 v[60:63], v[146:149], v[218:221], v[60:63]
	v_mfma_f32_16x16x32_bf16 v[52:55], v[154:157], v[218:221], v[52:55]
	ds_read_b128 v[178:181], v144 offset:32768
	v_mfma_f32_16x16x32_bf16 v[44:47], v[146:149], v[226:229], v[44:47]
	v_mfma_f32_16x16x32_bf16 v[36:39], v[154:157], v[226:229], v[36:39]
	v_mfma_f32_16x16x32_bf16 v[28:31], v[146:149], v[234:237], v[28:31]
	v_mfma_f32_16x16x32_bf16 v[20:23], v[154:157], v[234:237], v[20:23]
	ds_read_b128 v[182:185], v144 offset:33792
	v_mfma_f32_16x16x32_bf16 v[12:15], v[146:149], v[242:245], v[12:15]
	v_mfma_f32_16x16x32_bf16 v[4:7], v[154:157], v[242:245], v[4:7]
	v_mfma_f32_16x16x32_bf16 v[60:63], v[150:153], v[222:225], v[60:63]
	v_mfma_f32_16x16x32_bf16 v[52:55], v[158:161], v[222:225], v[52:55]
	ds_read_b128 v[186:189], v144 offset:34816
	v_mfma_f32_16x16x32_bf16 v[44:47], v[150:153], v[230:233], v[44:47]
	v_mfma_f32_16x16x32_bf16 v[36:39], v[158:161], v[230:233], v[36:39]
	v_mfma_f32_16x16x32_bf16 v[28:31], v[150:153], v[238:241], v[28:31]
	v_mfma_f32_16x16x32_bf16 v[20:23], v[158:161], v[238:241], v[20:23]
	ds_read_b128 v[190:193], v144 offset:35840
	v_mfma_f32_16x16x32_bf16 v[12:15], v[150:153], v[246:249], v[12:15]
	v_mfma_f32_16x16x32_bf16 v[4:7], v[158:161], v[246:249], v[4:7]
	s_setprio 0
	s_setprio 1
	v_mfma_f32_16x16x32_bf16 v[56:59], v[162:165], v[218:221], v[56:59]
	v_mfma_f32_16x16x32_bf16 v[48:51], v[170:173], v[218:221], v[48:51]
	ds_read_b128 v[194:197], v144 offset:36864
	v_mfma_f32_16x16x32_bf16 v[40:43], v[162:165], v[226:229], v[40:43]
	v_mfma_f32_16x16x32_bf16 v[32:35], v[170:173], v[226:229], v[32:35]
	v_mfma_f32_16x16x32_bf16 v[24:27], v[162:165], v[234:237], v[24:27]
	v_mfma_f32_16x16x32_bf16 v[16:19], v[170:173], v[234:237], v[16:19]
	ds_read_b128 v[200:203], v144 offset:37888
	v_mfma_f32_16x16x32_bf16 v[8:11], v[162:165], v[242:245], v[8:11]
	v_mfma_f32_16x16x32_bf16 v[0:3], v[170:173], v[242:245], v[0:3]
	v_mfma_f32_16x16x32_bf16 v[56:59], v[166:169], v[222:225], v[56:59]
	v_mfma_f32_16x16x32_bf16 v[48:51], v[174:177], v[222:225], v[48:51]
	ds_read_b128 v[206:209], v144 offset:38912
	v_mfma_f32_16x16x32_bf16 v[40:43], v[166:169], v[230:233], v[40:43]
	v_mfma_f32_16x16x32_bf16 v[32:35], v[174:177], v[230:233], v[32:35]
	v_mfma_f32_16x16x32_bf16 v[24:27], v[166:169], v[238:241], v[24:27]
	v_mfma_f32_16x16x32_bf16 v[16:19], v[174:177], v[238:241], v[16:19]
	ds_read_b128 v[210:213], v144 offset:39936
	v_mfma_f32_16x16x32_bf16 v[8:11], v[166:169], v[246:249], v[8:11]
	v_mfma_f32_16x16x32_bf16 v[0:3], v[174:177], v[246:249], v[0:3]
	s_setprio 0
	s_barrier
	s_add_i32 s30, 0, 0x18000
	v_add_u32_e32 v145, s30, v142
	s_add_i32 s31, 0, 0x1c000
	ds_read_b128 v[146:149], v145
	ds_read_b128 v[150:153], v145 offset:1024
	ds_read_b128 v[154:157], v145 offset:2048
	ds_read_b128 v[158:161], v145 offset:3072
	v_add_u32_e32 v145, s31, v142
	ds_read_b128 v[162:165], v145
	ds_read_b128 v[166:169], v145 offset:1024
	ds_read_b128 v[170:173], v145 offset:2048
	ds_read_b128 v[174:177], v145 offset:3072
	s_add_u32 s28, s66, 0x80000
	s_addc_u32 s29, s67, 0
	s_mov_b32 m0, s61
	s_nop 0
	global_load_lds_dwordx4 v136, s[28:29]
	s_mov_b32 m0, s70
	s_nop 0
	global_load_lds_dwordx4 v132, s[28:29]
	s_waitcnt vmcnt(8)
	s_waitcnt lgkmcnt(0)
	s_barrier
; #define PG8_STAGE(bufoff, gbase, voff) do { _Pragma("unroll") for (int _i = 0; _i < 2; ++_i) \
;         __builtin_amdgcn_global_load_lds((const unsigned*)((const char*)(gbase) + (voff)[_i]), (PG8_LAS unsigned*)(lds + (bufoff) + ldsw + _i * 8192), 16, 0, 0); } while (0)
; #define PG8_LDA(dst, b, h) do { _Pragma("unroll") for (int m = 0; m < 4; ++m) _Pragma("unroll") for (int k = 0; k < 2; ++k) dst[m][k] = *(const PG8_LAS bf16x8*)(lds + PG8_SA(b, h) + aoff + m * 2048 + k * 1024); } while (0)
; #define PG8_MMA(ai, bj, At, Bt) do { __builtin_amdgcn_s_setprio(1); _Pragma("unroll") for (int m = 0; m < 4; ++m) _Pragma("unroll") for (int n = 0; n < 2; ++n) _Pragma("unroll") for (int k = 0; k < 2; ++k) \
;         acc[ai][bj][m][n] = __builtin_amdgcn_mfma_f32_16x16x32_bf16(Bt[n][k], At[m][k], acc[ai][bj][m][n], 0, 0, 0); __builtin_amdgcn_s_setprio(0); } while (0)
; #define PG8_WAIT_V(n) asm volatile("s_waitcnt vmcnt(" #n ")" ::: "memory")
; #define PG8_WAIT_L(n) asm volatile("s_waitcnt lgkmcnt(" #n ")" ::: "memory")
; #define PG8_BAR __builtin_amdgcn_s_barrier()
; #define PG8_SCHED __builtin_amdgcn_sched_barrier(0)
; template <class Epi, class Sched, bool ALIGN_EPI = true, bool SP2 = true>
; __device__ __forceinline__ void gemm_phase(PG8_LAS unsigned char* lds, const Gemm g, const Sched& S, const Epi& E, const int tid) {
;     ...
;             PG8_WAIT_V(8); PG8_WAIT_L(0); PG8_BAR; PG8_MMA(0, 0, At, B0); PG8_MMA(0, 1, At, B1); PG8_BAR; PG8_SCHED;
;             PG8_LDA(At, 1, 1); PG8_STAGE(PG8_SB(1, 0), b3, voffB); PG8_STAGE(PG8_SB(1, 1), b3 + hstepB, voffB); PG8_STAGE(PG8_SA(1, 0), a3, voffA);
;             PG8_WAIT_V(8); PG8_WAIT_L(0); PG8_BAR; PG8_MMA(1, 0, At, B0); PG8_MMA(1, 1, At, B1); PG8_BAR; PG8_SCHED;
	s_setprio 1
	s_waitcnt lgkmcnt(0)
	v_mfma_f32_16x16x32_bf16 v[126:129], v[146:149], v[178:181], v[126:129]
	v_mfma_f32_16x16x32_bf16 v[118:121], v[154:157], v[178:181], v[118:121]
	ds_read_b128 v[218:221], v144 offset:49152
	v_mfma_f32_16x16x32_bf16 v[110:113], v[146:149], v[186:189], v[110:113]
	v_mfma_f32_16x16x32_bf16 v[102:105], v[154:157], v[186:189], v[102:105]
	v_mfma_f32_16x16x32_bf16 v[92:95], v[146:149], v[194:197], v[92:95]
	v_mfma_f32_16x16x32_bf16 v[84:87], v[154:157], v[194:197], v[84:87]
	ds_read_b128 v[222:225], v144 offset:50176
	v_mfma_f32_16x16x32_bf16 v[76:79], v[146:149], v[206:209], v[76:79]
	v_mfma_f32_16x16x32_bf16 v[68:71], v[154:157], v[206:209], v[68:71]
	v_mfma_f32_16x16x32_bf16 v[126:129], v[150:153], v[182:185], v[126:129]
	v_mfma_f32_16x16x32_bf16 v[118:121], v[158:161], v[182:185], v[118:121]
	ds_read_b128 v[226:229], v144 offset:51200
	v_mfma_f32_16x16x32_bf16 v[110:113], v[150:153], v[190:193], v[110:113]
	v_mfma_f32_16x16x32_bf16 v[102:105], v[158:161], v[190:193], v[102:105]
	v_mfma_f32_16x16x32_bf16 v[92:95], v[150:153], v[200:203], v[92:95]
	v_mfma_f32_16x16x32_bf16 v[84:87], v[158:161], v[200:203], v[84:87]
	ds_read_b128 v[230:233], v144 offset:52224
	v_mfma_f32_16x16x32_bf16 v[76:79], v[150:153], v[210:213], v[76:79]
	v_mfma_f32_16x16x32_bf16 v[68:71], v[158:161], v[210:213], v[68:71]
	s_setprio 0
	s_setprio 1
	v_mfma_f32_16x16x32_bf16 v[122:125], v[162:165], v[178:181], v[122:125]
	v_mfma_f32_16x16x32_bf16 v[114:117], v[170:173], v[178:181], v[114:117]
	ds_read_b128 v[234:237], v144 offset:53248
	v_mfma_f32_16x16x32_bf16 v[106:109], v[162:165], v[186:189], v[106:109]
	v_mfma_f32_16x16x32_bf16 v[98:101], v[170:173], v[186:189], v[98:101]
	v_mfma_f32_16x16x32_bf16 v[88:91], v[162:165], v[194:197], v[88:91]
	v_mfma_f32_16x16x32_bf16 v[80:83], v[170:173], v[194:197], v[80:83]
	ds_read_b128 v[238:241], v144 offset:54272
	v_mfma_f32_16x16x32_bf16 v[72:75], v[162:165], v[206:209], v[72:75]
	v_mfma_f32_16x16x32_bf16 v[64:67], v[170:173], v[206:209], v[64:67]
	v_mfma_f32_16x16x32_bf16 v[122:125], v[166:169], v[182:185], v[122:125]
	v_mfma_f32_16x16x32_bf16 v[114:117], v[174:177], v[182:185], v[114:117]
	ds_read_b128 v[242:245], v144 offset:55296
	v_mfma_f32_16x16x32_bf16 v[106:109], v[166:169], v[190:193], v[106:109]
	v_mfma_f32_16x16x32_bf16 v[98:101], v[174:177], v[190:193], v[98:101]
	v_mfma_f32_16x16x32_bf16 v[88:91], v[166:169], v[200:203], v[88:91]
	v_mfma_f32_16x16x32_bf16 v[80:83], v[174:177], v[200:203], v[80:83]
	ds_read_b128 v[246:249], v144 offset:56320
	v_mfma_f32_16x16x32_bf16 v[72:75], v[166:169], v[210:213], v[72:75]
	v_mfma_f32_16x16x32_bf16 v[64:67], v[174:177], v[210:213], v[64:67]
	s_setprio 0
	s_barrier
	s_add_u32 s4, s66, 0x80
	s_addc_u32 s5, s67, 0
	s_mov_b32 m0, s71
	s_nop 0
	global_load_lds_dwordx4 v136, s[4:5]
	s_mov_b32 m0, s72
	s_nop 0
	global_load_lds_dwordx4 v132, s[4:5]
	s_add_i32 s28, s30, s21
	s_add_u32 s4, s64, 0x80
	s_addc_u32 s5, s65, 0
	s_mov_b32 m0, s28
	s_nop 0
	global_load_lds_dwordx4 v134, s[4:5]
	s_add_i32 m0, s28, 0x2000
	s_add_u32 s28, s64, 0x80080
	s_addc_u32 s29, s65, 0
	s_add_i32 s30, s31, s21
	global_load_lds_dwordx4 v130, s[4:5]
	s_mov_b32 m0, s30
	s_nop 0
	global_load_lds_dwordx4 v134, s[28:29]
	s_add_i32 m0, s30, 0x2000
	s_nop 0
	global_load_lds_dwordx4 v130, s[28:29]
	s_waitcnt vmcnt(6)
	s_waitcnt lgkmcnt(0)
	s_barrier
	s_setprio 1
	s_waitcnt lgkmcnt(0)
	v_mfma_f32_16x16x32_bf16 v[60:63], v[146:149], v[218:221], v[60:63]
	v_mfma_f32_16x16x32_bf16 v[52:55], v[154:157], v[218:221], v[52:55]
	v_mfma_f32_16x16x32_bf16 v[44:47], v[146:149], v[226:229], v[44:47]
	v_mfma_f32_16x16x32_bf16 v[36:39], v[154:157], v[226:229], v[36:39]
	v_mfma_f32_16x16x32_bf16 v[28:31], v[146:149], v[234:237], v[28:31]
	v_mfma_f32_16x16x32_bf16 v[20:23], v[154:157], v[234:237], v[20:23]
	v_mfma_f32_16x16x32_bf16 v[12:15], v[146:149], v[242:245], v[12:15]
	v_mfma_f32_16x16x32_bf16 v[4:7], v[154:157], v[242:245], v[4:7]
	v_mfma_f32_16x16x32_bf16 v[60:63], v[150:153], v[222:225], v[60:63]
	v_mfma_f32_16x16x32_bf16 v[52:55], v[158:161], v[222:225], v[52:55]
	v_mfma_f32_16x16x32_bf16 v[44:47], v[150:153], v[230:233], v[44:47]
	v_mfma_f32_16x16x32_bf16 v[36:39], v[158:161], v[230:233], v[36:39]
	v_mfma_f32_16x16x32_bf16 v[28:31], v[150:153], v[238:241], v[28:31]
	v_mfma_f32_16x16x32_bf16 v[20:23], v[158:161], v[238:241], v[20:23]
	v_mfma_f32_16x16x32_bf16 v[12:15], v[150:153], v[246:249], v[12:15]
	v_mfma_f32_16x16x32_bf16 v[4:7], v[158:161], v[246:249], v[4:7]
	s_setprio 0
	s_setprio 1
	v_mfma_f32_16x16x32_bf16 v[56:59], v[162:165], v[218:221], v[56:59]
	v_mfma_f32_16x16x32_bf16 v[48:51], v[170:173], v[218:221], v[48:51]
	v_mfma_f32_16x16x32_bf16 v[40:43], v[162:165], v[226:229], v[40:43]
	v_mfma_f32_16x16x32_bf16 v[32:35], v[170:173], v[226:229], v[32:35]
	v_mfma_f32_16x16x32_bf16 v[24:27], v[162:165], v[234:237], v[24:27]
	v_mfma_f32_16x16x32_bf16 v[16:19], v[170:173], v[234:237], v[16:19]
	v_mfma_f32_16x16x32_bf16 v[8:11], v[162:165], v[242:245], v[8:11]
	v_mfma_f32_16x16x32_bf16 v[0:3], v[170:173], v[242:245], v[0:3]
	v_mfma_f32_16x16x32_bf16 v[56:59], v[166:169], v[222:225], v[56:59]
	v_mfma_f32_16x16x32_bf16 v[48:51], v[174:177], v[222:225], v[48:51]
	v_mfma_f32_16x16x32_bf16 v[40:43], v[166:169], v[230:233], v[40:43]
	v_mfma_f32_16x16x32_bf16 v[32:35], v[174:177], v[230:233], v[32:35]
	v_mfma_f32_16x16x32_bf16 v[24:27], v[166:169], v[238:241], v[24:27]
	v_mfma_f32_16x16x32_bf16 v[16:19], v[174:177], v[238:241], v[16:19]
	v_mfma_f32_16x16x32_bf16 v[8:11], v[166:169], v[246:249], v[8:11]
	v_mfma_f32_16x16x32_bf16 v[0:3], v[174:177], v[246:249], v[0:3]
	s_setprio 0
	s_barrier
	s_add_i32 s52, s52, 2
	s_add_u32 s62, s62, 0x100
	s_addc_u32 s63, s63, 0
	s_add_u32 s49, s49, 0x100
	s_addc_u32 s51, s51, 0
	s_cmp_gt_u32 s52, 29
	s_cbranch_scc0 .LBB0_1319
	v_mov_b32_e32 v218, 0x2a00
	v_mov_b32_e32 v219, 0xf149f2ca
	v_mov_b32_e32 v220, 0xe00
	s_mov_b64 s[4:5], 0x80
	s_and_b64 vcc, exec, s[46:47]
	s_cbranch_vccz .LBB0_1322
	s_barrier

; #define PG8_STAGE(bufoff, gbase, voff) do { _Pragma("unroll") for (int _i = 0; _i < 2; ++_i) \
;         __builtin_amdgcn_global_load_lds((const unsigned*)((const char*)(gbase) + (voff)[_i]), (PG8_LAS unsigned*)(lds + (bufoff) + ldsw + _i * 8192), 16, 0, 0); } while (0)
; #define PG8_LDA(dst, b, h) do { _Pragma("unroll") for (int m = 0; m < 4; ++m) _Pragma("unroll") for (int k = 0; k < 2; ++k) dst[m][k] = *(const PG8_LAS bf16x8*)(lds + PG8_SA(b, h) + aoff + m * 2048 + k * 1024); } while (0)
; #define PG8_LDB(dst, b, h) do { _Pragma("unroll") for (int n = 0; n < 2; ++n) _Pragma("unroll") for (int k = 0; k < 2; ++k) dst[n][k] = *(const PG8_LAS bf16x8*)(lds + PG8_SB(b, h) + boff + n * 2048 + k * 1024); } while (0)
; #define PG8_MMA(ai, bj, At, Bt) do { __builtin_amdgcn_s_setprio(1); _Pragma("unroll") for (int m = 0; m < 4; ++m) _Pragma("unroll") for (int n = 0; n < 2; ++n) _Pragma("unroll") for (int k = 0; k < 2; ++k) \
;         acc[ai][bj][m][n] = __builtin_amdgcn_mfma_f32_16x16x32_bf16(Bt[n][k], At[m][k], acc[ai][bj][m][n], 0, 0, 0); __builtin_amdgcn_s_setprio(0); } while (0)
; #define PG8_WAIT_V(n) asm volatile("s_waitcnt vmcnt(" #n ")" ::: "memory")
; #define PG8_BAR __builtin_amdgcn_s_barrier()
; template <class Epi, class Sched, bool ALIGN_EPI = true, bool SP2 = true>
; __device__ __forceinline__ void gemm_phase(PG8_LAS unsigned char* lds, const Gemm g, const Sched& S, const Epi& E, const int tid) {
;     ...
;         for (int t = 0; t < nt; t += 2) {
;             const bool last = (t == nt - 2);
;             const char* a1 = cA + (size_t)(t + 1) * kstep;
;             const char* a2 = last ? nA : cA + (size_t)(t + 2) * kstep; const char* b2 = last ? nB : cB + (size_t)(t + 2) * kstep;
;             const char* a3 = a2 + kstep; const char* b3 = b2 + kstep;
;             if (last && has_next) S.a_ready(nxt);
;             if constexpr (SP2) {
;             PG8_LDB(B0, 0, 0); PG8_LDB(B1, 0, 1); PG8_SCHED; PG8_LDA(At, 0, 0); PG8_STAGE(PG8_SA(1, 1), a1 + hstepA, voffA);
;             PG8_WAIT_V(8); PG8_WAIT_L(0); PG8_BAR; PG8_MMA(0, 0, At, B0); PG8_MMA(0, 1, At, B1); PG8_BAR; PG8_SCHED;
;             PG8_LDA(At, 0, 1); PG8_STAGE(PG8_SB(0, 0), b2, voffB); PG8_STAGE(PG8_SB(0, 1), b2 + hstepB, voffB); PG8_STAGE(PG8_SA(0, 0), a2, voffA);
;             PG8_WAIT_V(8); PG8_WAIT_L(0); PG8_BAR; PG8_MMA(1, 0, At, B0); PG8_MMA(1, 1, At, B1); PG8_BAR; PG8_SCHED;
.LBB0_1523:
	s_add_i32 vcc_lo, s72, 2
	s_add_u32 s70, s82, 0x100
	s_addc_u32 s71, s83, 0
	s_add_i32 s30, 0, 0x10000
	s_cmp_eq_u32 s29, s72
	s_cselect_b32 s81, s63, s71
	s_cselect_b32 s80, s62, s70
	v_add_u32_e32 v96, s30, v141
	s_cselect_b32 s73, s65, s59
	s_cselect_b32 s72, s64, s57
	s_add_i32 s31, 0, 0x14000
	ds_read_b128 v[146:149], v96
	ds_read_b128 v[150:153], v96 offset:1024
	ds_read_b128 v[154:157], v96 offset:2048
	ds_read_b128 v[158:161], v96 offset:3072
	v_add_u32_e32 v96, s31, v141
	ds_read_b128 v[162:165], v96
	ds_read_b128 v[166:169], v96 offset:1024
	ds_read_b128 v[170:173], v96 offset:2048
	ds_read_b128 v[174:177], v96 offset:3072
	s_add_i32 m0, s23, 0xc000
	ds_read_b128 v[178:181], v145
	ds_read_b128 v[182:185], v145 offset:1024
	ds_read_b128 v[186:189], v145 offset:2048
	ds_read_b128 v[190:193], v145 offset:3072
	ds_read_b128 v[194:197], v145 offset:4096
	ds_read_b128 v[200:203], v145 offset:5120
	ds_read_b128 v[206:209], v145 offset:6144
	ds_read_b128 v[210:213], v145 offset:7168
	global_load_lds_dwordx4 v136, s[82:83]
	s_add_i32 m0, s23, 0xe000
	s_nop 0
	global_load_lds_dwordx4 v138, s[82:83]
	s_waitcnt vmcnt(4)
	s_waitcnt lgkmcnt(0)
	s_barrier
	s_setprio 1
	s_waitcnt lgkmcnt(0)
	v_mfma_f32_16x16x32_bf16 v[52:55], v[146:149], v[178:181], v[52:55]
	v_mfma_f32_16x16x32_bf16 v[56:59], v[154:157], v[178:181], v[56:59]
	ds_read_b128 v[224:227], v145 offset:16384
	v_mfma_f32_16x16x32_bf16 v[104:107], v[146:149], v[186:189], v[104:107]
	v_mfma_f32_16x16x32_bf16 v[84:87], v[154:157], v[186:189], v[84:87]
	v_mfma_f32_16x16x32_bf16 v[110:113], v[146:149], v[194:197], v[110:113]
	v_mfma_f32_16x16x32_bf16 v[98:101], v[154:157], v[194:197], v[100:103]
	ds_read_b128 v[228:231], v145 offset:17408
	v_mfma_f32_16x16x32_bf16 v[88:91], v[146:149], v[206:209], v[88:91]
	v_mfma_f32_16x16x32_bf16 v[80:83], v[154:157], v[206:209], v[80:83]
	v_mfma_f32_16x16x32_bf16 v[52:55], v[150:153], v[182:185], v[52:55]
	v_mfma_f32_16x16x32_bf16 v[56:59], v[158:161], v[182:185], v[56:59]
	ds_read_b128 v[232:235], v145 offset:18432
	v_mfma_f32_16x16x32_bf16 v[104:107], v[150:153], v[190:193], v[104:107]
	v_mfma_f32_16x16x32_bf16 v[84:87], v[158:161], v[190:193], v[84:87]
	v_mfma_f32_16x16x32_bf16 v[110:113], v[150:153], v[200:203], v[110:113]
	v_mfma_f32_16x16x32_bf16 v[98:101], v[158:161], v[200:203], v[98:101]
	ds_read_b128 v[236:239], v145 offset:19456
	v_mfma_f32_16x16x32_bf16 v[88:91], v[150:153], v[210:213], v[88:91]
	v_mfma_f32_16x16x32_bf16 v[80:83], v[158:161], v[210:213], v[80:83]
	s_setprio 0
	s_setprio 1
	v_mfma_f32_16x16x32_bf16 v[48:51], v[162:165], v[178:181], v[48:51]
	v_mfma_f32_16x16x32_bf16 v[44:47], v[170:173], v[178:181], v[44:47]
	ds_read_b128 v[240:243], v145 offset:20480
	v_mfma_f32_16x16x32_bf16 v[76:79], v[162:165], v[186:189], v[76:79]
	v_mfma_f32_16x16x32_bf16 v[68:71], v[170:173], v[186:189], v[68:71]
	v_mfma_f32_16x16x32_bf16 v[130:133], v[162:165], v[194:197], v[130:133]
	v_mfma_f32_16x16x32_bf16 v[92:95], v[170:173], v[194:197], v[92:95]
	ds_read_b128 v[244:247], v145 offset:21504
	v_mfma_f32_16x16x32_bf16 v[72:75], v[162:165], v[206:209], v[72:75]
	v_mfma_f32_16x16x32_bf16 v[64:67], v[170:173], v[206:209], v[64:67]
	v_mfma_f32_16x16x32_bf16 v[48:51], v[166:169], v[182:185], v[48:51]
	v_mfma_f32_16x16x32_bf16 v[44:47], v[174:177], v[182:185], v[44:47]
	ds_read_b128 v[248:251], v145 offset:22528
	v_mfma_f32_16x16x32_bf16 v[76:79], v[166:169], v[190:193], v[76:79]
	v_mfma_f32_16x16x32_bf16 v[68:71], v[174:177], v[190:193], v[68:71]
	v_mfma_f32_16x16x32_bf16 v[130:133], v[166:169], v[200:203], v[130:133]
	v_mfma_f32_16x16x32_bf16 v[92:95], v[174:177], v[200:203], v[92:95]
	v_mfma_f32_16x16x32_bf16 v[72:75], v[166:169], v[210:213], v[72:75]
	v_mfma_f32_16x16x32_bf16 v[64:67], v[174:177], v[210:213], v[64:67]
	s_setprio 0
	s_barrier
	s_add_i32 s30, s30, s22
	s_mov_b32 m0, s30
	ds_read_b128 v[210:213], v145 offset:23552
	global_load_lds_dwordx4 v108, s[72:73]
	s_add_i32 m0, s30, 0x2000
	s_add_u32 s82, s72, 0x160000
	s_addc_u32 s83, s73, 0
	s_add_i32 s30, s31, s22
	global_load_lds_dwordx4 v134, s[72:73]
	s_mov_b32 m0, s30
	s_nop 0
	global_load_lds_dwordx4 v108, s[82:83]
	s_add_i32 m0, s30, 0x2000
	s_nop 0
	global_load_lds_dwordx4 v134, s[82:83]
	s_mov_b32 m0, s23
	s_nop 0
	global_load_lds_dwordx4 v108, s[80:81]
	s_mov_b32 m0, s24
	s_nop 0
	global_load_lds_dwordx4 v134, s[80:81]
	s_waitcnt vmcnt(6)
	s_waitcnt lgkmcnt(0)
	s_barrier
; #define PG8_STAGE(bufoff, gbase, voff) do { _Pragma("unroll") for (int _i = 0; _i < 2; ++_i) \
;         __builtin_amdgcn_global_load_lds((const unsigned*)((const char*)(gbase) + (voff)[_i]), (PG8_LAS unsigned*)(lds + (bufoff) + ldsw + _i * 8192), 16, 0, 0); } while (0)
; #define PG8_LDA(dst, b, h) do { _Pragma("unroll") for (int m = 0; m < 4; ++m) _Pragma("unroll") for (int k = 0; k < 2; ++k) dst[m][k] = *(const PG8_LAS bf16x8*)(lds + PG8_SA(b, h) + aoff + m * 2048 + k * 1024); } while (0)
; #define PG8_LDB(dst, b, h) do { _Pragma("unroll") for (int n = 0; n < 2; ++n) _Pragma("unroll") for (int k = 0; k < 2; ++k) dst[n][k] = *(const PG8_LAS bf16x8*)(lds + PG8_SB(b, h) + boff + n * 2048 + k * 1024); } while (0)
; #define PG8_MMA(ai, bj, At, Bt) do { __builtin_amdgcn_s_setprio(1); _Pragma("unroll") for (int m = 0; m < 4; ++m) _Pragma("unroll") for (int n = 0; n < 2; ++n) _Pragma("unroll") for (int k = 0; k < 2; ++k) \
;         acc[ai][bj][m][n] = __builtin_amdgcn_mfma_f32_16x16x32_bf16(Bt[n][k], At[m][k], acc[ai][bj][m][n], 0, 0, 0); __builtin_amdgcn_s_setprio(0); } while (0)
; #define PG8_WAIT_V(n) asm volatile("s_waitcnt vmcnt(" #n ")" ::: "memory")
; #define PG8_WAIT_L(n) asm volatile("s_waitcnt lgkmcnt(" #n ")" ::: "memory")
; #define PG8_BAR __builtin_amdgcn_s_barrier()
; #define PG8_SCHED __builtin_amdgcn_sched_barrier(0)
; template <class Epi, class Sched, bool ALIGN_EPI = true, bool SP2 = true>
; __device__ __forceinline__ void gemm_phase(PG8_LAS unsigned char* lds, const Gemm g, const Sched& S, const Epi& E, const int tid) {
;     ...
;             PG8_WAIT_V(8); PG8_WAIT_L(0); PG8_BAR; PG8_MMA(1, 0, At, B0); PG8_MMA(1, 1, At, B1); PG8_BAR; PG8_SCHED;
;             PG8_LDB(B0, 1, 0); PG8_LDB(B1, 1, 1); PG8_SCHED; PG8_LDA(At, 1, 0); PG8_STAGE(PG8_SA(0, 1), a2 + hstepA, voffA);
	s_setprio 1
	s_waitcnt lgkmcnt(0)
	v_mfma_f32_16x16x32_bf16 v[126:129], v[146:149], v[224:227], v[126:129]
	v_mfma_f32_16x16x32_bf16 v[122:125], v[154:157], v[224:227], v[122:125]
	ds_read_b128 v[178:181], v145 offset:32768
	v_mfma_f32_16x16x32_bf16 v[60:63], v[146:149], v[232:235], v[60:63]
	v_mfma_f32_16x16x32_bf16 v[40:43], v[154:157], v[232:235], v[40:43]
	v_mfma_f32_16x16x32_bf16 v[28:31], v[146:149], v[240:243], v[28:31]
	v_mfma_f32_16x16x32_bf16 v[24:27], v[154:157], v[240:243], v[24:27]
	ds_read_b128 v[182:185], v145 offset:33792
	v_mfma_f32_16x16x32_bf16 v[12:15], v[146:149], v[248:251], v[12:15]
	v_mfma_f32_16x16x32_bf16 v[8:11], v[154:157], v[248:251], v[8:11]
	v_mfma_f32_16x16x32_bf16 v[126:129], v[150:153], v[228:231], v[126:129]
	v_mfma_f32_16x16x32_bf16 v[122:125], v[158:161], v[228:231], v[122:125]
	ds_read_b128 v[186:189], v145 offset:34816
	v_mfma_f32_16x16x32_bf16 v[60:63], v[150:153], v[236:239], v[60:63]
	v_mfma_f32_16x16x32_bf16 v[40:43], v[158:161], v[236:239], v[40:43]
	v_mfma_f32_16x16x32_bf16 v[28:31], v[150:153], v[244:247], v[28:31]
	v_mfma_f32_16x16x32_bf16 v[24:27], v[158:161], v[244:247], v[24:27]
	ds_read_b128 v[190:193], v145 offset:35840
	v_mfma_f32_16x16x32_bf16 v[12:15], v[150:153], v[210:213], v[12:15]
	v_mfma_f32_16x16x32_bf16 v[8:11], v[158:161], v[210:213], v[8:11]
	s_setprio 0
	s_setprio 1
	v_mfma_f32_16x16x32_bf16 v[118:121], v[162:165], v[224:227], v[118:121]
	v_mfma_f32_16x16x32_bf16 v[114:117], v[170:173], v[224:227], v[114:117]
	ds_read_b128 v[194:197], v145 offset:36864
	v_mfma_f32_16x16x32_bf16 v[36:39], v[162:165], v[232:235], v[36:39]
	v_mfma_f32_16x16x32_bf16 v[32:35], v[170:173], v[232:235], v[32:35]
	v_mfma_f32_16x16x32_bf16 v[20:23], v[162:165], v[240:243], v[20:23]
	v_mfma_f32_16x16x32_bf16 v[16:19], v[170:173], v[240:243], v[16:19]
	ds_read_b128 v[200:203], v145 offset:37888
	v_mfma_f32_16x16x32_bf16 v[4:7], v[162:165], v[248:251], v[4:7]
	v_mfma_f32_16x16x32_bf16 v[0:3], v[170:173], v[248:251], v[0:3]
	v_mfma_f32_16x16x32_bf16 v[118:121], v[166:169], v[228:231], v[118:121]
	v_mfma_f32_16x16x32_bf16 v[114:117], v[174:177], v[228:231], v[114:117]
	ds_read_b128 v[206:209], v145 offset:38912
	v_mfma_f32_16x16x32_bf16 v[36:39], v[166:169], v[236:239], v[36:39]
	v_mfma_f32_16x16x32_bf16 v[32:35], v[174:177], v[236:239], v[32:35]
	v_mfma_f32_16x16x32_bf16 v[20:23], v[166:169], v[244:247], v[20:23]
	v_mfma_f32_16x16x32_bf16 v[16:19], v[174:177], v[244:247], v[16:19]
	v_mfma_f32_16x16x32_bf16 v[4:7], v[166:169], v[210:213], v[4:7]
	v_mfma_f32_16x16x32_bf16 v[0:3], v[174:177], v[210:213], v[0:3]
	s_setprio 0
	s_barrier
	s_add_i32 s30, 0, 0x18000
	v_add_u32_e32 v96, s30, v141
	s_add_i32 s31, 0, 0x1c000
	ds_read_b128 v[146:149], v96
	ds_read_b128 v[150:153], v96 offset:1024
	ds_read_b128 v[154:157], v96 offset:2048
	ds_read_b128 v[158:161], v96 offset:3072
	v_add_u32_e32 v96, s31, v141
	ds_read_b128 v[162:165], v96
	ds_read_b128 v[166:169], v96 offset:1024
	ds_read_b128 v[170:173], v96 offset:2048
	ds_read_b128 v[174:177], v96 offset:3072
	s_add_u32 s80, s80, 0x160000
	s_addc_u32 s81, s81, 0
	s_mov_b32 m0, s25
	ds_read_b128 v[210:213], v145 offset:39936
	global_load_lds_dwordx4 v108, s[80:81]
	s_mov_b32 m0, s49
	s_nop 0
	global_load_lds_dwordx4 v134, s[80:81]
	s_waitcnt vmcnt(8)
	s_waitcnt lgkmcnt(0)
	s_barrier
; #define PG8_STAGE(bufoff, gbase, voff) do { _Pragma("unroll") for (int _i = 0; _i < 2; ++_i) \
;         __builtin_amdgcn_global_load_lds((const unsigned*)((const char*)(gbase) + (voff)[_i]), (PG8_LAS unsigned*)(lds + (bufoff) + ldsw + _i * 8192), 16, 0, 0); } while (0)
; #define PG8_LDA(dst, b, h) do { _Pragma("unroll") for (int m = 0; m < 4; ++m) _Pragma("unroll") for (int k = 0; k < 2; ++k) dst[m][k] = *(const PG8_LAS bf16x8*)(lds + PG8_SA(b, h) + aoff + m * 2048 + k * 1024); } while (0)
; #define PG8_MMA(ai, bj, At, Bt) do { __builtin_amdgcn_s_setprio(1); _Pragma("unroll") for (int m = 0; m < 4; ++m) _Pragma("unroll") for (int n = 0; n < 2; ++n) _Pragma("unroll") for (int k = 0; k < 2; ++k) \
;         acc[ai][bj][m][n] = __builtin_amdgcn_mfma_f32_16x16x32_bf16(Bt[n][k], At[m][k], acc[ai][bj][m][n], 0, 0, 0); __builtin_amdgcn_s_setprio(0); } while (0)
; #define PG8_WAIT_V(n) asm volatile("s_waitcnt vmcnt(" #n ")" ::: "memory")
; #define PG8_WAIT_L(n) asm volatile("s_waitcnt lgkmcnt(" #n ")" ::: "memory")
; #define PG8_BAR __builtin_amdgcn_s_barrier()
; #define PG8_SCHED __builtin_amdgcn_sched_barrier(0)
; template <class Epi, class Sched, bool ALIGN_EPI = true, bool SP2 = true>
; __device__ __forceinline__ void gemm_phase(PG8_LAS unsigned char* lds, const Gemm g, const Sched& S, const Epi& E, const int tid) {
;     ...
;             PG8_WAIT_V(8); PG8_WAIT_L(0); PG8_BAR; PG8_MMA(0, 0, At, B0); PG8_MMA(0, 1, At, B1); PG8_BAR; PG8_SCHED;
;             PG8_LDA(At, 1, 1); PG8_STAGE(PG8_SB(1, 0), b3, voffB); PG8_STAGE(PG8_SB(1, 1), b3 + hstepB, voffB); PG8_STAGE(PG8_SA(1, 0), a3, voffA);
;             PG8_WAIT_V(8); PG8_WAIT_L(0); PG8_BAR; PG8_MMA(1, 0, At, B0); PG8_MMA(1, 1, At, B1); PG8_BAR; PG8_SCHED;
	s_setprio 1
	s_waitcnt lgkmcnt(0)
	v_mfma_f32_16x16x32_bf16 v[52:55], v[146:149], v[178:181], v[52:55]
	v_mfma_f32_16x16x32_bf16 v[56:59], v[154:157], v[178:181], v[56:59]
	ds_read_b128 v[224:227], v145 offset:49152
	v_mfma_f32_16x16x32_bf16 v[102:105], v[146:149], v[186:189], v[104:107]
	v_mfma_f32_16x16x32_bf16 v[84:87], v[154:157], v[186:189], v[84:87]
	v_mfma_f32_16x16x32_bf16 v[110:113], v[146:149], v[194:197], v[110:113]
	v_mfma_f32_16x16x32_bf16 v[98:101], v[154:157], v[194:197], v[98:101]
	ds_read_b128 v[228:231], v145 offset:50176
	v_mfma_f32_16x16x32_bf16 v[88:91], v[146:149], v[206:209], v[88:91]
	v_mfma_f32_16x16x32_bf16 v[80:83], v[154:157], v[206:209], v[80:83]
	v_mfma_f32_16x16x32_bf16 v[52:55], v[150:153], v[182:185], v[52:55]
	v_mfma_f32_16x16x32_bf16 v[56:59], v[158:161], v[182:185], v[56:59]
	ds_read_b128 v[232:235], v145 offset:51200
	v_mfma_f32_16x16x32_bf16 v[104:107], v[150:153], v[190:193], v[102:105]
	v_mfma_f32_16x16x32_bf16 v[84:87], v[158:161], v[190:193], v[84:87]
	v_mfma_f32_16x16x32_bf16 v[110:113], v[150:153], v[200:203], v[110:113]
	v_mfma_f32_16x16x32_bf16 v[100:103], v[158:161], v[200:203], v[98:101]
	ds_read_b128 v[236:239], v145 offset:52224
	v_mfma_f32_16x16x32_bf16 v[88:91], v[150:153], v[210:213], v[88:91]
	v_mfma_f32_16x16x32_bf16 v[80:83], v[158:161], v[210:213], v[80:83]
	s_setprio 0
	s_setprio 1
	v_mfma_f32_16x16x32_bf16 v[48:51], v[162:165], v[178:181], v[48:51]
	v_mfma_f32_16x16x32_bf16 v[44:47], v[170:173], v[178:181], v[44:47]
	ds_read_b128 v[240:243], v145 offset:53248
	v_mfma_f32_16x16x32_bf16 v[76:79], v[162:165], v[186:189], v[76:79]
	v_mfma_f32_16x16x32_bf16 v[68:71], v[170:173], v[186:189], v[68:71]
	v_mfma_f32_16x16x32_bf16 v[130:133], v[162:165], v[194:197], v[130:133]
	v_mfma_f32_16x16x32_bf16 v[92:95], v[170:173], v[194:197], v[92:95]
	ds_read_b128 v[244:247], v145 offset:54272
	v_mfma_f32_16x16x32_bf16 v[72:75], v[162:165], v[206:209], v[72:75]
	v_mfma_f32_16x16x32_bf16 v[64:67], v[170:173], v[206:209], v[64:67]
	v_mfma_f32_16x16x32_bf16 v[48:51], v[166:169], v[182:185], v[48:51]
	v_mfma_f32_16x16x32_bf16 v[44:47], v[174:177], v[182:185], v[44:47]
	ds_read_b128 v[248:251], v145 offset:55296
	v_mfma_f32_16x16x32_bf16 v[76:79], v[166:169], v[190:193], v[76:79]
	v_mfma_f32_16x16x32_bf16 v[68:71], v[174:177], v[190:193], v[68:71]
	v_mfma_f32_16x16x32_bf16 v[130:133], v[166:169], v[200:203], v[130:133]
	v_mfma_f32_16x16x32_bf16 v[92:95], v[174:177], v[200:203], v[92:95]
	v_mfma_f32_16x16x32_bf16 v[72:75], v[166:169], v[210:213], v[72:75]
	v_mfma_f32_16x16x32_bf16 v[64:67], v[174:177], v[210:213], v[64:67]
	s_setprio 0
	s_barrier
	s_add_u32 s4, s80, 0xffea0080
	s_addc_u32 s5, s81, -1
	s_mov_b32 m0, s91
	s_nop 0
	global_load_lds_dwordx4 v108, s[4:5]
	s_mov_b32 m0, s86
	s_nop 0
	global_load_lds_dwordx4 v134, s[4:5]
	s_add_i32 s30, s30, s22
	s_add_u32 s4, s72, 0x80
	s_addc_u32 s5, s73, 0
	s_mov_b32 m0, s30
	ds_read_b128 v[210:213], v145 offset:56320
	global_load_lds_dwordx4 v108, s[4:5]
	s_add_i32 m0, s30, 0x2000
	s_add_u32 s72, s72, 0x160080
	s_addc_u32 s73, s73, 0
	s_add_i32 s30, s31, s22
	global_load_lds_dwordx4 v134, s[4:5]
	s_mov_b32 m0, s30
	s_nop 0
	global_load_lds_dwordx4 v108, s[72:73]
	s_add_i32 m0, s30, 0x2000
	s_nop 0
	global_load_lds_dwordx4 v134, s[72:73]
	s_waitcnt vmcnt(6)
	s_waitcnt lgkmcnt(0)
	s_barrier
	s_setprio 1
	s_waitcnt lgkmcnt(0)
	v_mfma_f32_16x16x32_bf16 v[126:129], v[146:149], v[224:227], v[126:129]
	v_mfma_f32_16x16x32_bf16 v[122:125], v[154:157], v[224:227], v[122:125]
	v_mfma_f32_16x16x32_bf16 v[60:63], v[146:149], v[232:235], v[60:63]
	v_mfma_f32_16x16x32_bf16 v[40:43], v[154:157], v[232:235], v[40:43]
	v_mfma_f32_16x16x32_bf16 v[28:31], v[146:149], v[240:243], v[28:31]
	v_mfma_f32_16x16x32_bf16 v[24:27], v[154:157], v[240:243], v[24:27]
	v_mfma_f32_16x16x32_bf16 v[12:15], v[146:149], v[248:251], v[12:15]
	v_mfma_f32_16x16x32_bf16 v[8:11], v[154:157], v[248:251], v[8:11]
	v_mfma_f32_16x16x32_bf16 v[126:129], v[150:153], v[228:231], v[126:129]
	v_mfma_f32_16x16x32_bf16 v[122:125], v[158:161], v[228:231], v[122:125]
	v_mfma_f32_16x16x32_bf16 v[60:63], v[150:153], v[236:239], v[60:63]
	v_mfma_f32_16x16x32_bf16 v[40:43], v[158:161], v[236:239], v[40:43]
	v_mfma_f32_16x16x32_bf16 v[28:31], v[150:153], v[244:247], v[28:31]
	v_mfma_f32_16x16x32_bf16 v[24:27], v[158:161], v[244:247], v[24:27]
	v_mfma_f32_16x16x32_bf16 v[12:15], v[150:153], v[210:213], v[12:15]
	v_mfma_f32_16x16x32_bf16 v[8:11], v[158:161], v[210:213], v[8:11]
	s_setprio 0
	s_setprio 1
	v_mfma_f32_16x16x32_bf16 v[118:121], v[162:165], v[224:227], v[118:121]
	v_mfma_f32_16x16x32_bf16 v[114:117], v[170:173], v[224:227], v[114:117]
	v_mfma_f32_16x16x32_bf16 v[36:39], v[162:165], v[232:235], v[36:39]
	v_mfma_f32_16x16x32_bf16 v[32:35], v[170:173], v[232:235], v[32:35]
	v_mfma_f32_16x16x32_bf16 v[20:23], v[162:165], v[240:243], v[20:23]
	v_mfma_f32_16x16x32_bf16 v[16:19], v[170:173], v[240:243], v[16:19]
	v_mfma_f32_16x16x32_bf16 v[4:7], v[162:165], v[248:251], v[4:7]
	v_mfma_f32_16x16x32_bf16 v[0:3], v[170:173], v[248:251], v[0:3]
	v_mfma_f32_16x16x32_bf16 v[118:121], v[166:169], v[228:231], v[118:121]
	v_mfma_f32_16x16x32_bf16 v[114:117], v[174:177], v[228:231], v[114:117]
	v_mfma_f32_16x16x32_bf16 v[36:39], v[166:169], v[236:239], v[36:39]
	v_mfma_f32_16x16x32_bf16 v[32:35], v[174:177], v[236:239], v[32:35]
	v_mfma_f32_16x16x32_bf16 v[20:23], v[166:169], v[244:247], v[20:23]
	v_mfma_f32_16x16x32_bf16 v[16:19], v[174:177], v[244:247], v[16:19]
	v_mfma_f32_16x16x32_bf16 v[4:7], v[166:169], v[210:213], v[4:7]
	v_mfma_f32_16x16x32_bf16 v[0:3], v[174:177], v[210:213], v[0:3]
	s_setprio 0
	s_barrier
	s_add_u32 s57, s57, 0x100
	s_addc_u32 s59, s59, 0
	s_cmp_ge_i32 vcc_lo, s53
	s_mov_b64 s[82:83], s[70:71]
	s_mov_b32 s72, vcc_lo
	s_cbranch_scc0 .LBB0_1523
	s_mov_b64 s[4:5], 0x80
